# attention: s_setprio 1 around the QK^T and PV MFMA clusters (on top of k-inner GEMM order)
# speedup vs baseline: 1.0045x; 1.0004x over previous
; #define LAS __attribute__((address_space(3)))
; __device__ __forceinline__ void qkt(f32x16& p0, f32x16& p1, const LAS char* K_buf, int r32, int hi, const bf16x8* qr) {
;     ...
;     for (int d0 = 0; d0 < 8; ++d0) { const LAS char* ap = kb[d0 & 3] + (d0 >> 2) * 128;
;         const bf16x8 b0 = *(const LAS bf16x8*)ap;
;         const bf16x8 b1 = *(const LAS bf16x8*)(ap + 32 * 256);
;         const bf16x8 qf = qr[d0];
;         p0 = __builtin_amdgcn_mfma_f32_32x32x16_bf16(b0, qf, p0, 0, 0, 0);
;         p1 = __builtin_amdgcn_mfma_f32_32x32x16_bf16(b1, qf, p1, 0, 0, 0); }
; template <bool SBK>
; __device__ __forceinline__ void attn_unit(const Args& a, int l, LAS char* lds, int b, int h8, int P0, int orow0, int nvalid) {
;     ...
;  for (int r = 0; r < 16; ++r) { const int c = (r & 3) + 8 * (r >> 2);
;                     float z = p0[r]; float lv = -(fmaxf(z, 0.f) + __builtin_amdgcn_logf(1.0f + __builtin_amdgcn_exp2f(-fabsf(z)))); if (needmask && (dq - c < 1)) lv = 0.f; l0[r] = lv;
;                     z = p1[r]; lv = -(fmaxf(z, 0.f) + __builtin_amdgcn_logf(1.0f + __builtin_amdgcn_exp2f(-fabsf(z)))); if (needmask && (dq - c - 32 < 1)) lv = 0.f; l1[r] = lv; }
.LBB0_458:
	s_lshl_b32 s7, s1, 14
	v_add_u32_e32 v0, s7, v165
	v_add_u32_e32 v10, v0, v166
	ds_read_b128 v[2:5], v10 offset:49152
	ds_read_b128 v[6:9], v10 offset:57344
	v_add_u32_e32 v11, v0, v167
	v_add_u32_e32 v12, v0, v168
	v_add_u32_e32 v0, v0, v169
	s_waitcnt lgkmcnt(0)
	s_setprio 1
	v_mfma_f32_32x32x16_bf16 v[96:111], v[2:5], v[112:115], 0
	v_mfma_f32_32x32x16_bf16 v[80:95], v[6:9], v[112:115], 0
	ds_read_b128 v[2:5], v11 offset:49152
	ds_read_b128 v[6:9], v11 offset:57344
	s_waitcnt lgkmcnt(0)
	v_mfma_f32_32x32x16_bf16 v[96:111], v[2:5], v[116:119], v[96:111]
	v_mfma_f32_32x32x16_bf16 v[80:95], v[6:9], v[116:119], v[80:95]
	ds_read_b128 v[2:5], v12 offset:49152
	ds_read_b128 v[6:9], v12 offset:57344
	s_waitcnt lgkmcnt(0)
	v_mfma_f32_32x32x16_bf16 v[96:111], v[2:5], v[120:123], v[96:111]
	v_mfma_f32_32x32x16_bf16 v[80:95], v[6:9], v[120:123], v[80:95]
	ds_read_b128 v[2:5], v0 offset:49152
	ds_read_b128 v[6:9], v0 offset:57344
	s_waitcnt lgkmcnt(0)
	v_mfma_f32_32x32x16_bf16 v[96:111], v[2:5], v[124:127], v[96:111]
	v_mfma_f32_32x32x16_bf16 v[80:95], v[6:9], v[124:127], v[80:95]
	ds_read_b128 v[2:5], v10 offset:49280
	ds_read_b128 v[6:9], v10 offset:57472
	s_waitcnt lgkmcnt(0)
	v_mfma_f32_32x32x16_bf16 v[96:111], v[2:5], v[128:131], v[96:111]
	v_mfma_f32_32x32x16_bf16 v[80:95], v[6:9], v[128:131], v[80:95]
	ds_read_b128 v[2:5], v11 offset:49280
	ds_read_b128 v[6:9], v11 offset:57472
	s_waitcnt lgkmcnt(0)
	v_mfma_f32_32x32x16_bf16 v[96:111], v[2:5], v[132:135], v[96:111]
	v_mfma_f32_32x32x16_bf16 v[80:95], v[6:9], v[132:135], v[80:95]
	ds_read_b128 v[2:5], v12 offset:49280
	ds_read_b128 v[6:9], v12 offset:57472
	s_waitcnt lgkmcnt(0)
	v_mfma_f32_32x32x16_bf16 v[96:111], v[2:5], v[136:139], v[96:111]
	v_mfma_f32_32x32x16_bf16 v[80:95], v[6:9], v[136:139], v[80:95]
	ds_read_b128 v[2:5], v0 offset:49280
	ds_read_b128 v[6:9], v0 offset:57472
	v_or_b32_e32 v0, s0, v160
	s_or_b32 s0, s0, 63
	s_cmp_lt_i32 s0, s26
	s_cselect_b64 s[22:23], -1, 0
	s_waitcnt lgkmcnt(0)
	v_mfma_f32_32x32x16_bf16 v[96:111], v[2:5], v[140:143], v[96:111]
	v_sub_u32_e32 v3, v164, v0
	v_cmp_lt_i32_e32 vcc, 0, v3
	s_or_b64 s[0:1], s[22:23], vcc
	v_cmp_lt_i32_e32 vcc, 32, v3
	s_or_b64 s[40:41], s[22:23], vcc
	v_cmp_lt_i32_e32 vcc, 1, v3
	s_or_b64 s[42:43], s[22:23], vcc
	v_mfma_f32_32x32x16_bf16 v[80:95], v[6:9], v[140:143], v[80:95]
	s_setprio 0
	s_nop 3
	v_exp_f32_e64 v2, -|v96|
	v_exp_f32_e64 v5, -|v97|
	v_max_f32_e32 v0, v96, v96
	v_max_f32_e32 v0, 0, v0
	v_add_f32_e32 v2, 1.0, v2
	v_log_f32_e32 v2, v2
	v_add_f32_e32 v5, 1.0, v5
	s_nop 0
	v_exp_f32_e64 v4, -|v80|
	v_exp_f32_e64 v6, -|v81|
	v_add_f32_e32 v0, v0, v2
	v_cndmask_b32_e64 v2, 0, -v0, s[0:1]
	v_add_f32_e32 v4, 1.0, v4
	v_log_f32_e32 v4, v4
	v_max_f32_e32 v0, v80, v80
	v_log_f32_e32 v5, v5
	v_max_f32_e32 v0, 0, v0
	v_add_f32_e32 v6, 1.0, v6
	v_add_f32_e32 v0, v0, v4
	v_max_f32_e32 v4, v97, v97
	v_log_f32_e32 v6, v6
	v_max_f32_e32 v4, 0, v4
	v_add_f32_e32 v4, v4, v5
	v_max_f32_e32 v5, v81, v81
	v_max_f32_e32 v5, 0, v5
	v_add_f32_e32 v5, v5, v6
	v_exp_f32_e64 v6, -|v98|
	v_exp_f32_e64 v7, -|v82|
	v_cmp_lt_i32_e32 vcc, 33, v3
	s_or_b64 s[44:45], s[22:23], vcc
	v_add_f32_e32 v6, 1.0, v6
	v_log_f32_e32 v6, v6
	v_cndmask_b32_e64 v171, 0, -v5, s[44:45]
	v_max_f32_e32 v5, v98, v98
	v_add_f32_e32 v7, 1.0, v7
	v_max_f32_e32 v5, 0, v5
	v_cmp_lt_i32_e32 vcc, 2, v3
	v_log_f32_e32 v7, v7
	v_add_f32_e32 v5, v5, v6
	s_or_b64 s[46:47], s[22:23], vcc
	v_cndmask_b32_e64 v6, 0, -v5, s[46:47]
	v_max_f32_e32 v5, v82, v82
	v_max_f32_e32 v5, 0, v5
	v_add_f32_e32 v5, v5, v7
	v_exp_f32_e64 v7, -|v99|
	v_cmp_lt_i32_e32 vcc, 34, v3
	s_or_b64 s[48:49], s[22:23], vcc
	v_cndmask_b32_e64 v172, 0, -v5, s[48:49]
	v_add_f32_e32 v7, 1.0, v7
	v_log_f32_e32 v7, v7
	v_max_f32_e32 v5, v99, v99
	v_max_f32_e32 v5, 0, v5
	v_cmp_lt_i32_e32 vcc, 3, v3
	v_add_f32_e32 v5, v5, v7
	v_exp_f32_e64 v7, -|v83|
	s_or_b64 s[52:53], s[22:23], vcc
	v_cndmask_b32_e64 v8, 0, -v5, s[52:53]
	v_max_f32_e32 v5, v83, v83
	v_add_f32_e32 v7, 1.0, v7
	v_log_f32_e32 v7, v7
	v_max_f32_e32 v5, 0, v5
	v_cmp_lt_i32_e32 vcc, 35, v3
	s_or_b64 s[56:57], s[22:23], vcc
	v_add_f32_e32 v5, v5, v7
	v_exp_f32_e64 v7, -|v100|
	v_cndmask_b32_e64 v175, 0, -v5, s[56:57]
	v_max_f32_e32 v5, v100, v100
	v_max_f32_e32 v5, 0, v5
	v_add_f32_e32 v7, 1.0, v7
	v_log_f32_e32 v7, v7
	v_cmp_lt_i32_e32 vcc, 8, v3
	s_or_b64 s[50:51], s[22:23], vcc
	v_cmp_lt_i32_e32 vcc, 40, v3
	v_add_f32_e32 v5, v5, v7
	v_exp_f32_e64 v7, -|v84|
	v_cndmask_b32_e64 v173, 0, -v5, s[50:51]
	v_max_f32_e32 v5, v84, v84
	v_max_f32_e32 v5, 0, v5
	v_add_f32_e32 v7, 1.0, v7
	v_log_f32_e32 v7, v7
	s_or_b64 s[54:55], s[22:23], vcc
	v_cmp_lt_i32_e32 vcc, 9, v3
	s_or_b64 s[58:59], s[22:23], vcc
	v_add_f32_e32 v5, v5, v7
	v_exp_f32_e64 v7, -|v101|
	v_cndmask_b32_e64 v174, 0, -v5, s[54:55]
	v_max_f32_e32 v5, v101, v101
	v_max_f32_e32 v5, 0, v5
	v_add_f32_e32 v7, 1.0, v7
	v_log_f32_e32 v7, v7
	v_cmp_lt_i32_e32 vcc, 41, v3
	s_or_b64 s[60:61], s[22:23], vcc
	v_cmp_lt_i32_e32 vcc, 10, v3
	v_add_f32_e32 v5, v5, v7
	v_exp_f32_e64 v7, -|v85|
	v_cndmask_b32_e64 v176, 0, -v5, s[58:59]
	v_max_f32_e32 v5, v85, v85
	v_max_f32_e32 v5, 0, v5
	v_add_f32_e32 v7, 1.0, v7
	v_log_f32_e32 v7, v7
	s_or_b64 s[62:63], s[22:23], vcc
	v_cmp_lt_i32_e32 vcc, 42, v3
	s_or_b64 s[64:65], s[22:23], vcc
	v_add_f32_e32 v5, v5, v7
	v_exp_f32_e64 v7, -|v102|
	v_cndmask_b32_e64 v177, 0, -v5, s[60:61]
	v_max_f32_e32 v5, v102, v102
	v_max_f32_e32 v5, 0, v5
	v_add_f32_e32 v7, 1.0, v7
	v_log_f32_e32 v7, v7
	v_cmp_lt_i32_e32 vcc, 11, v3
	s_or_b64 s[68:69], s[22:23], vcc
	v_cmp_lt_i32_e32 vcc, 43, v3
	v_add_f32_e32 v5, v5, v7
	v_exp_f32_e64 v7, -|v86|
	v_cndmask_b32_e64 v178, 0, -v5, s[62:63]
; __device__ __forceinline__ float pair_other(float x, int hi) { auto rr = __builtin_amdgcn_permlane32_swap(__float_as_uint(x), __float_as_uint(x), false, false); return __uint_as_float(hi ? rr[0] : rr[1]); }
; template <bool SBK>
; __device__ __forceinline__ void attn_unit(const Args& a, int l, LAS char* lds, int b, int h8, int P0, int orow0, int nvalid) {
;     ...
;                     float z = p0[r]; float lv = -(fmaxf(z, 0.f) + __builtin_amdgcn_logf(1.0f + __builtin_amdgcn_exp2f(-fabsf(z)))); if (needmask && (dq - c < 1)) lv = 0.f; l0[r] = lv;
;                     z = p1[r]; lv = -(fmaxf(z, 0.f) + __builtin_amdgcn_logf(1.0f + __builtin_amdgcn_exp2f(-fabsf(z)))); if (needmask && (dq - c - 32 < 1)) lv = 0.f; l1[r] = lv; }
;                 float gs[8], pg[8], aft[8];
; #pragma unroll
;  for (int i = 0; i < 4; ++i) { gs[i] = (l0[4 * i] + l0[4 * i + 1]) + (l0[4 * i + 2] + l0[4 * i + 3]); gs[4 + i] = (l1[4 * i] + l1[4 * i + 1]) + (l1[4 * i + 2] + l1[4 * i + 3]); }
; #pragma unroll
;  for (int i = 0; i < 8; ++i) pg[i] = pair_other(gs[i], hi);
	v_max_f32_e32 v5, v86, v86
	v_max_f32_e32 v5, 0, v5
	v_add_f32_e32 v7, 1.0, v7
	v_log_f32_e32 v7, v7
	s_or_b64 s[72:73], s[22:23], vcc
	v_cmp_lt_i32_e32 vcc, 16, v3
	s_or_b64 s[66:67], s[22:23], vcc
	v_add_f32_e32 v5, v5, v7
	v_exp_f32_e64 v7, -|v103|
	v_cndmask_b32_e64 v179, 0, -v5, s[64:65]
	v_max_f32_e32 v5, v103, v103
	v_max_f32_e32 v5, 0, v5
	v_add_f32_e32 v7, 1.0, v7
	v_log_f32_e32 v7, v7
	v_cmp_lt_i32_e32 vcc, 48, v3
	s_or_b64 s[70:71], s[22:23], vcc
	v_cmp_lt_i32_e32 vcc, 17, v3
	v_add_f32_e32 v5, v5, v7
	v_exp_f32_e64 v7, -|v87|
	v_cndmask_b32_e64 v181, 0, -v5, s[68:69]
	v_max_f32_e32 v5, v87, v87
	v_max_f32_e32 v5, 0, v5
	v_add_f32_e32 v7, 1.0, v7
	v_log_f32_e32 v7, v7
	s_or_b64 s[74:75], s[22:23], vcc
	v_cmp_lt_i32_e32 vcc, 49, v3
	s_or_b64 s[76:77], s[22:23], vcc
	v_add_f32_e32 v5, v5, v7
	v_exp_f32_e64 v7, -|v104|
	v_cndmask_b32_e64 v182, 0, -v5, s[72:73]
	v_max_f32_e32 v5, v104, v104
	v_max_f32_e32 v5, 0, v5
	v_add_f32_e32 v7, 1.0, v7
	v_log_f32_e32 v7, v7
	v_cmp_lt_i32_e32 vcc, 18, v3
	s_or_b64 s[78:79], s[22:23], vcc
	v_cmp_lt_i32_e32 vcc, 50, v3
	v_add_f32_e32 v5, v5, v7
	v_exp_f32_e64 v7, -|v88|
	v_cndmask_b32_e64 v180, 0, -v5, s[66:67]
	v_max_f32_e32 v5, v88, v88
	v_max_f32_e32 v5, 0, v5
	v_add_f32_e32 v7, 1.0, v7
	v_log_f32_e32 v7, v7
	s_or_b64 s[80:81], s[22:23], vcc
	v_cmp_lt_i32_e32 vcc, 19, v3
	s_or_b64 s[84:85], s[22:23], vcc
	v_add_f32_e32 v5, v5, v7
	v_exp_f32_e64 v7, -|v105|
	v_cndmask_b32_e64 v10, 0, -v5, s[70:71]
	v_max_f32_e32 v5, v105, v105
	v_max_f32_e32 v5, 0, v5
	v_add_f32_e32 v7, 1.0, v7
	v_log_f32_e32 v7, v7
	v_cmp_lt_i32_e32 vcc, 51, v3
	s_or_b64 s[88:89], s[22:23], vcc
	v_cmp_lt_i32_e32 vcc, 24, v3
	v_add_f32_e32 v5, v5, v7
	v_exp_f32_e64 v7, -|v89|
	v_cndmask_b32_e64 v183, 0, -v5, s[74:75]
	v_max_f32_e32 v5, v89, v89
	v_max_f32_e32 v5, 0, v5
	v_add_f32_e32 v7, 1.0, v7
	v_log_f32_e32 v7, v7
	s_or_b64 s[82:83], s[22:23], vcc
	v_cmp_lt_i32_e32 vcc, 56, v3
	s_or_b64 s[86:87], s[22:23], vcc
	v_add_f32_e32 v5, v5, v7
	v_exp_f32_e64 v7, -|v106|
	v_cndmask_b32_e64 v12, 0, -v5, s[76:77]
	v_max_f32_e32 v5, v106, v106
	v_max_f32_e32 v5, 0, v5
	v_add_f32_e32 v7, 1.0, v7
	v_log_f32_e32 v7, v7
	v_cmp_lt_i32_e32 vcc, 25, v3
	s_or_b64 s[90:91], s[22:23], vcc
	v_cmp_lt_i32_e32 vcc, 57, v3
	v_add_f32_e32 v5, v5, v7
	v_exp_f32_e64 v7, -|v90|
	v_cndmask_b32_e64 v184, 0, -v5, s[78:79]
	v_max_f32_e32 v5, v90, v90
	v_max_f32_e32 v5, 0, v5
	v_add_f32_e32 v7, 1.0, v7
	v_log_f32_e32 v7, v7
	s_or_b64 s[92:93], s[22:23], vcc
	v_cmp_lt_i32_e32 vcc, 26, v3
	s_or_b64 s[94:95], s[22:23], vcc
	v_add_f32_e32 v5, v5, v7
	v_exp_f32_e64 v7, -|v107|
	v_cndmask_b32_e64 v185, 0, -v5, s[80:81]
	v_max_f32_e32 v5, v107, v107
	v_max_f32_e32 v5, 0, v5
	v_add_f32_e32 v7, 1.0, v7
	v_log_f32_e32 v7, v7
	v_cmp_lt_i32_e32 vcc, 58, v3
	s_or_b64 s[96:97], s[22:23], vcc
	v_cmp_lt_i32_e32 vcc, 27, v3
	v_add_f32_e32 v5, v5, v7
	v_exp_f32_e64 v7, -|v91|
	v_cndmask_b32_e64 v194, 0, -v5, s[84:85]
	v_max_f32_e32 v5, v91, v91
	v_max_f32_e32 v5, 0, v5
	v_add_f32_e32 v7, 1.0, v7
	v_log_f32_e32 v7, v7
	s_or_b64 s[4:5], s[22:23], vcc
	v_cmp_lt_i32_e32 vcc, 59, v3
	v_cndmask_b32_e64 v0, 0, -v0, s[40:41]
	v_add_f32_e32 v5, v5, v7
	v_exp_f32_e64 v7, -|v108|
	v_cndmask_b32_e64 v196, 0, -v5, s[88:89]
	v_max_f32_e32 v5, v108, v108
	v_max_f32_e32 v5, 0, v5
	v_add_f32_e32 v7, 1.0, v7
	v_log_f32_e32 v7, v7
	s_or_b64 vcc, s[22:23], vcc
	v_add_f32_e32 v3, v0, v171
	v_add_f32_e32 v9, v184, v194
	v_add_f32_e32 v5, v5, v7
	v_exp_f32_e64 v7, -|v92|
	v_cndmask_b32_e64 v14, 0, -v5, s[82:83]
	v_max_f32_e32 v5, v92, v92
	v_max_f32_e32 v5, 0, v5
	v_add_f32_e32 v7, 1.0, v7
	v_log_f32_e32 v7, v7
	v_add_f32_e32 v186, v185, v196
	v_cndmask_b32_e64 v4, 0, -v4, s[42:43]
	v_add_f32_e32 v5, v5, v7
	v_exp_f32_e64 v7, -|v109|
	v_cndmask_b32_e64 v195, 0, -v5, s[86:87]
	v_max_f32_e32 v5, v109, v109
	v_max_f32_e32 v5, 0, v5
	v_add_f32_e32 v7, 1.0, v7
	v_log_f32_e32 v7, v7
	s_nop 0
	v_add_f32_e32 v5, v5, v7
	v_exp_f32_e64 v7, -|v93|
	v_cndmask_b32_e64 v154, 0, -v5, s[90:91]
	v_max_f32_e32 v5, v93, v93
	v_max_f32_e32 v5, 0, v5
	v_add_f32_e32 v7, 1.0, v7
	v_log_f32_e32 v7, v7
	s_nop 0
	v_add_f32_e32 v5, v5, v7
	v_exp_f32_e64 v7, -|v110|
	v_cndmask_b32_e64 v197, 0, -v5, s[92:93]
	v_max_f32_e32 v5, v110, v110
	v_max_f32_e32 v5, 0, v5
	v_add_f32_e32 v7, 1.0, v7
	v_log_f32_e32 v7, v7
	v_add_f32_e32 v11, v195, v197
	v_add_f32_e32 v5, v5, v7
	v_exp_f32_e64 v7, -|v94|
	v_cndmask_b32_e64 v156, 0, -v5, s[94:95]
	v_max_f32_e32 v5, v94, v94
	v_max_f32_e32 v5, 0, v5
	v_add_f32_e32 v7, 1.0, v7
	v_log_f32_e32 v7, v7
	s_nop 0
	v_add_f32_e32 v5, v5, v7
	v_exp_f32_e64 v7, -|v111|
	v_cndmask_b32_e64 v190, 0, -v5, s[96:97]
	v_max_f32_e32 v5, v111, v111
	v_max_f32_e32 v5, 0, v5
	v_add_f32_e32 v7, 1.0, v7
	v_log_f32_e32 v7, v7
	s_nop 0
	v_add_f32_e32 v5, v5, v7
	v_exp_f32_e64 v7, -|v95|
	v_cndmask_b32_e64 v158, 0, -v5, s[4:5]
	v_max_f32_e32 v5, v95, v95
	v_max_f32_e32 v5, 0, v5
	v_add_f32_e32 v7, 1.0, v7
	v_log_f32_e32 v7, v7
	s_nop 0
	v_add_f32_e32 v5, v5, v7
	v_cndmask_b32_e64 v191, 0, -v5, vcc
	v_add_f32_e32 v5, v172, v175
	v_add_f32_e32 v15, v3, v5
	v_add_f32_e32 v3, v173, v176
	v_add_f32_e32 v5, v178, v181
	v_add_f32_e32 v3, v3, v5
	v_add_f32_e32 v5, v174, v177
	v_add_f32_e32 v7, v179, v182
	v_add_f32_e32 v7, v5, v7
	v_add_f32_e32 v5, v180, v183
	v_add_f32_e32 v192, v5, v9
	v_add_f32_e32 v13, v190, v191
	v_mov_b32_e32 v5, v3
	v_mov_b32_e32 v9, v3
	s_nop 1
	v_permlane32_swap_b32_e32 v5, v9
	v_pk_add_f32 v[188:189], v[10:11], v[12:13]
	v_cndmask_b32_e64 v5, v5, v9, s[36:37]
	v_mov_b32_e32 v9, v192
	v_mov_b32_e32 v152, v192
	v_mov_b32_e32 v11, v189
	v_mov_b32_e32 v13, v189
	v_permlane32_swap_b32_e32 v9, v152
; __device__ __forceinline__ float pair_other(float x, int hi) { auto rr = __builtin_amdgcn_permlane32_swap(__float_as_uint(x), __float_as_uint(x), false, false); return __uint_as_float(hi ? rr[0] : rr[1]); }
; template <bool SBK>
; __device__ __forceinline__ void attn_unit(const Args& a, int l, LAS char* lds, int b, int h8, int P0, int orow0, int nvalid) {
;     ...
;  for (int i = 0; i < 8; ++i) pg[i] = pair_other(gs[i], hi);
;                 float run = R;
; #pragma unroll
;  for (int i = 7; i >= 0; --i) { aft[i] = run + (hi ? 0.f : pg[i]); run += gs[i] + pg[i]; }
;                 R = run;
; #pragma unroll
;  for (int i = 0; i < 4; ++i) { float c0 = aft[i], c1 = aft[4 + i];
; #pragma unroll
;  for (int e = 3; e >= 0; --e) { const int r = 4 * i + e; const int c = (r & 3) + 8 * (r >> 2);
;                         c0 += l0[r]; float av = __builtin_amdgcn_exp2f(p0[r] + c0); if (needmask && (dq - c < 1)) av = 0.f; p0[r] = av;
;                         c1 += l1[r]; av = __builtin_amdgcn_exp2f(p1[r] + c1); if (needmask && (dq - c - 32 < 1)) av = 0.f; p1[r] = av; } }
	s_nop 0
	v_permlane32_swap_b32_e32 v11, v13
	v_cndmask_b32_e64 v193, v9, v152, s[36:37]
	v_mov_b32_e32 v9, v15
	v_mov_b32_e32 v152, v15
	v_cndmask_b32_e64 v187, v11, v13, s[36:37]
	s_nop 0
	v_permlane32_swap_b32_e32 v9, v152
	v_pk_add_f32 v[188:189], v[188:189], v[186:187]
	v_cndmask_b32_e64 v155, v9, v152, s[36:37]
	v_mov_b32_e32 v9, v7
	v_mov_b32_e32 v152, v7
	v_mov_b32_e32 v11, v188
	v_mov_b32_e32 v13, v188
	v_permlane32_swap_b32_e32 v9, v152
	s_nop 0
	v_permlane32_swap_b32_e32 v11, v13
	v_cndmask_b32_e64 v9, v9, v152, s[36:37]
	v_cndmask_b32_e64 v152, v11, v13, s[36:37]
	v_cndmask_b32_e64 v11, 0, v187, s[36:37]
	v_add_f32_e32 v11, v153, v11
	v_cndmask_b32_e64 v13, 0, v152, s[36:37]
	v_pk_add_f32 v[152:153], v[188:189], v[152:153]
	v_add_f32_e32 v157, v7, v9
	v_add_f32_e32 v13, v13, v153
	v_pk_add_f32 v[152:153], v[152:153], v[152:153] op_sel:[0,1] op_sel_hi:[1,0]
	v_pk_add_f32 v[186:187], v[14:15], v[154:155]
	v_cndmask_b32_e64 v153, 0, v9, s[36:37]
	v_mov_b32_e32 v159, v152
	v_add_f32_e32 v188, v153, v152
	v_pk_add_f32 v[152:153], v[156:157], v[158:159]
	v_cndmask_b32_e64 v7, 0, v155, s[36:37]
	v_pk_add_f32 v[186:187], v[186:187], v[152:153]
	v_add_f32_e32 v13, v196, v13
	v_mov_b32_e32 v9, v186
	v_mov_b32_e32 v15, v186
	s_nop 1
	v_permlane32_swap_b32_e32 v9, v15
	v_cndmask_b32_e64 v9, v9, v15, s[36:37]
	v_add_f32_e32 v15, v7, v153
	v_cndmask_b32_e64 v7, 0, v9, s[36:37]
	v_add_f32_e32 v155, v7, v187
	v_add_f32_e32 v7, v186, v9
	v_add_f32_e32 v9, v7, v187
	v_cndmask_b32_e64 v7, 0, v193, s[36:37]
	v_add_f32_e32 v157, v7, v9
	v_add_f32_e32 v7, v192, v193
	v_pk_add_f32 v[186:187], v[6:7], v[8:9]
	v_add_f32_e32 v9, v175, v15
	v_add_f32_e32 v15, v83, v9
	v_add_f32_e32 v9, v172, v9
	v_pk_add_f32 v[152:153], v[2:3], v[4:5]
	v_add_f32_e32 v82, v82, v9
	v_add_f32_e32 v9, v171, v9
	v_add_f32_e32 v91, v91, v13
	v_add_f32_e32 v13, v185, v13
	v_pk_add_f32 v[152:153], v[152:153], v[186:187]
	v_add_f32_e32 v81, v81, v9
	v_add_f32_e32 v0, v0, v9
	v_add_f32_e32 v9, v182, v188
	v_add_f32_e32 v12, v12, v13
	v_cndmask_b32_e64 v159, 0, v5, s[36:37]
	v_mov_b32_e32 v3, v152
	v_mov_b32_e32 v5, v152
	v_add_f32_e32 v0, v80, v0
	v_add_f32_e32 v80, v87, v9
	v_add_f32_e32 v9, v179, v9
	v_add_f32_e32 v90, v90, v13
	v_add_f32_e32 v13, v89, v12
	v_permlane32_swap_b32_e32 v3, v5
	v_add_f32_e32 v86, v86, v9
	v_add_f32_e32 v9, v177, v9
	v_exp_f32_e32 v13, v13
	v_cndmask_b32_e64 v3, v3, v5, s[36:37]
	v_add_f32_e32 v85, v85, v9
	v_add_f32_e32 v9, v174, v9
	v_add_f32_e32 v10, v10, v12
	v_cndmask_b32_e64 v7, 0, v3, s[36:37]
	v_add_f32_e32 v9, v84, v9
	v_add_f32_e32 v10, v88, v10
	v_add_f32_e32 v7, v7, v153
	v_exp_f32_e32 v9, v9
	v_exp_f32_e32 v10, v10
	v_add_f32_e32 v11, v191, v11
	v_add_f32_e32 v7, v8, v7
	v_cndmask_b32_e64 v89, 0, v13, s[76:77]
	v_add_f32_e32 v13, v95, v11
	v_add_f32_e32 v6, v6, v7
	v_exp_f32_e32 v13, v13
	v_add_f32_e32 v5, v159, v187
	v_add_f32_e32 v4, v4, v6
	v_add_f32_e32 v8, v99, v7
	v_add_f32_e32 v7, v98, v6
	v_add_f32_e32 v6, v97, v4
	v_add_f32_e32 v2, v2, v4
	v_add_f32_e32 v4, v181, v5
	v_cndmask_b32_e64 v84, 0, v9, s[54:55]
	v_add_f32_e32 v9, v194, v157
	v_cndmask_b32_e64 v88, 0, v10, s[70:71]
	v_add_f32_e32 v10, v158, v155
	v_add_f32_e32 v2, v96, v2
	v_add_f32_e32 v5, v103, v4
	v_add_f32_e32 v4, v178, v4
	v_add_f32_e32 v96, v107, v9
	v_add_f32_e32 v9, v184, v9
	v_add_f32_e32 v12, v111, v10
	v_add_f32_e32 v10, v156, v10
	v_add_f32_e32 v83, v102, v4
	v_add_f32_e32 v4, v176, v4
	v_add_f32_e32 v97, v106, v9
	v_add_f32_e32 v9, v183, v9
	v_cndmask_b32_e32 v95, 0, v13, vcc
	v_add_f32_e32 v13, v110, v10
	v_add_f32_e32 v11, v190, v11
	v_add_f32_e32 v10, v154, v10
	v_add_f32_e32 v87, v101, v4
	v_add_f32_e32 v4, v173, v4
	v_add_f32_e32 v98, v105, v9
	v_add_f32_e32 v9, v180, v9
	v_add_f32_e32 v94, v94, v11
	v_add_f32_e32 v99, v109, v10
	v_add_f32_e32 v11, v197, v11
	v_add_f32_e32 v10, v14, v10
	v_add_f32_e32 v4, v100, v4
	v_add_f32_e32 v9, v104, v9
	v_add_f32_e32 v93, v93, v11
	v_add_f32_e32 v10, v108, v10
	v_add_f32_e32 v11, v195, v11
	v_exp_f32_e32 v8, v8
	v_exp_f32_e32 v7, v7
	v_exp_f32_e32 v82, v82
	v_exp_f32_e32 v6, v6
	v_exp_f32_e32 v81, v81
	v_exp_f32_e32 v2, v2
	v_exp_f32_e32 v0, v0
	v_exp_f32_e32 v5, v5
	v_exp_f32_e32 v80, v80
	v_exp_f32_e32 v83, v83
	v_exp_f32_e32 v85, v85
	v_exp_f32_e32 v4, v4
	v_exp_f32_e32 v9, v9
	v_exp_f32_e32 v12, v12
	v_exp_f32_e32 v13, v13
	v_exp_f32_e32 v10, v10
	v_add_f32_e32 v11, v92, v11
	v_exp_f32_e32 v15, v15
	v_exp_f32_e32 v86, v86
	v_exp_f32_e32 v87, v87
	v_exp_f32_e32 v96, v96
	v_exp_f32_e32 v91, v91
	v_exp_f32_e32 v97, v97
	v_exp_f32_e32 v90, v90
	v_exp_f32_e32 v98, v98
	v_exp_f32_e32 v94, v94
	v_exp_f32_e32 v99, v99
	v_exp_f32_e32 v93, v93
	v_exp_f32_e32 v11, v11
	v_add_f32_e32 v3, v152, v3
	v_cndmask_b32_e64 v8, 0, v8, s[52:53]
	v_cndmask_b32_e64 v7, 0, v7, s[46:47]
	v_cndmask_b32_e64 v82, 0, v82, s[48:49]
; template <bool SBK>
; __device__ __forceinline__ void attn_unit(const Args& a, int l, LAS char* lds, int b, int h8, int P0, int orow0, int nvalid) {
;     ...
;                         c0 += l0[r]; float av = __builtin_amdgcn_exp2f(p0[r] + c0); if (needmask && (dq - c < 1)) av = 0.f; p0[r] = av;
;                         c1 += l1[r]; av = __builtin_amdgcn_exp2f(p1[r] + c1); if (needmask && (dq - c - 32 < 1)) av = 0.f; p1[r] = av; } }
;     ...
;             PK4(p0, 0, pa0); PK4(p0, 8, pa1); PK4(p1, 0, pa2); PK4(p1, 8, pa3);
;             pv_tile(o, vb0 + vb * SHM_V, pa0, pa1, pa2, pa3);
;         }
;         if constexpr (SBK) { const bool alive = __any(R > SB_EXIT); if (lane == 0) flag[(t & 1) * 8 + wid] = alive ? 1u : 0u; }
	v_cndmask_b32_e64 v6, 0, v6, s[42:43]
	v_cndmask_b32_e64 v81, 0, v81, s[44:45]
	v_cndmask_b32_e64 v2, 0, v2, s[0:1]
	v_cndmask_b32_e64 v0, 0, v0, s[40:41]
	v_cndmask_b32_e64 v5, 0, v5, s[68:69]
	v_cndmask_b32_e64 v80, 0, v80, s[72:73]
	v_cndmask_b32_e64 v83, 0, v83, s[62:63]
	v_cndmask_b32_e64 v85, 0, v85, s[60:61]
	v_cndmask_b32_e64 v4, 0, v4, s[50:51]
	v_cndmask_b32_e64 v9, 0, v9, s[66:67]
	v_cndmask_b32_e64 v12, 0, v12, s[4:5]
	v_cndmask_b32_e64 v13, 0, v13, s[94:95]
	v_cndmask_b32_e64 v10, 0, v10, s[82:83]
	v_cndmask_b32_e64 v15, 0, v15, s[56:57]
	v_cndmask_b32_e64 v86, 0, v86, s[64:65]
	v_cndmask_b32_e64 v87, 0, v87, s[58:59]
	v_cndmask_b32_e64 v96, 0, v96, s[84:85]
	v_cndmask_b32_e64 v91, 0, v91, s[88:89]
	v_cndmask_b32_e64 v97, 0, v97, s[78:79]
	v_cndmask_b32_e64 v90, 0, v90, s[80:81]
	v_cndmask_b32_e64 v98, 0, v98, s[74:75]
	v_cndmask_b32_e64 v94, 0, v94, s[96:97]
	v_cndmask_b32_e64 v99, 0, v99, s[90:91]
	v_cndmask_b32_e64 v93, 0, v93, s[92:93]
	v_cndmask_b32_e64 v14, 0, v11, s[86:87]
	v_add_f32_e32 v153, v3, v153
	v_cvt_pk_bf16_f32 v2, v2, v6
	v_cvt_pk_bf16_f32 v3, v7, v8
	v_cvt_pk_bf16_f32 v4, v4, v87
	v_cvt_pk_bf16_f32 v5, v83, v5
	v_cvt_pk_bf16_f32 v6, v9, v98
	v_cvt_pk_bf16_f32 v7, v97, v96
	v_cvt_pk_bf16_f32 v8, v10, v99
	v_cvt_pk_bf16_f32 v9, v13, v12
	v_cvt_pk_bf16_f32 v10, v0, v81
	v_cvt_pk_bf16_f32 v11, v82, v15
	v_cvt_pk_bf16_f32 v12, v84, v85
	v_cvt_pk_bf16_f32 v13, v86, v80
	v_cvt_pk_bf16_f32 v80, v88, v89
	v_cvt_pk_bf16_f32 v81, v90, v91
	v_cvt_pk_bf16_f32 v82, v14, v93
	v_cvt_pk_bf16_f32 v83, v94, v95
	v_add_u32_e32 v0, s7, v170
	ds_read_b64_tr_b16 v[84:85], v0 offset:0
	ds_read_b64_tr_b16 v[86:87], v0 offset:0x800
	ds_read_b64_tr_b16 v[88:89], v0 offset:0x1000
	ds_read_b64_tr_b16 v[90:91], v0 offset:0x1800
	ds_read_b64_tr_b16 v[92:93], v0 offset:0x2000
	ds_read_b64_tr_b16 v[94:95], v0 offset:0x2800
	ds_read_b64_tr_b16 v[96:97], v0 offset:0x3000
	ds_read_b64_tr_b16 v[98:99], v0 offset:0x3800
	ds_read_b64_tr_b16 v[100:101], v0 offset:0x200
	ds_read_b64_tr_b16 v[102:103], v0 offset:0xa00
	ds_read_b64_tr_b16 v[104:105], v0 offset:0x1200
	ds_read_b64_tr_b16 v[106:107], v0 offset:0x1a00
	ds_read_b64_tr_b16 v[108:109], v0 offset:0x2200
	ds_read_b64_tr_b16 v[110:111], v0 offset:0x2a00
	ds_read_b64_tr_b16 v[154:155], v0 offset:0x3200
	ds_read_b64_tr_b16 v[156:157], v0 offset:0x3a00
	s_waitcnt lgkmcnt(8)
	v_readlane_b32 s62, v255, 9
	v_readlane_b32 s63, v255, 10
	s_movk_i32 s61, 0x100
	v_readlane_b32 s60, v255, 8
	s_mov_b32 s81, 0xc2200000
	s_movk_i32 s80, 0x3000
	s_mov_b32 s82, 0xc2700000
	v_permlane32_swap_b32_e32 v2, v4
	v_permlane32_swap_b32_e32 v3, v5
	v_permlane32_swap_b32_e32 v6, v8
	v_permlane32_swap_b32_e32 v7, v9
	v_permlane32_swap_b32_e32 v10, v12
	v_permlane32_swap_b32_e32 v11, v13
	v_permlane32_swap_b32_e32 v80, v82
	v_permlane32_swap_b32_e32 v81, v83
	s_setprio 1
	v_mfma_f32_32x32x16_bf16 v[64:79], v[2:5], v[84:87], v[64:79]
	v_mfma_f32_32x32x16_bf16 v[64:79], v[6:9], v[88:91], v[64:79]
	v_mfma_f32_32x32x16_bf16 v[64:79], v[10:13], v[92:95], v[64:79]
	v_mfma_f32_32x32x16_bf16 v[64:79], v[80:83], v[96:99], v[64:79]
	ds_read_b64_tr_b16 v[84:85], v0 offset:0x400
	ds_read_b64_tr_b16 v[86:87], v0 offset:0xc00
	ds_read_b64_tr_b16 v[88:89], v0 offset:0x1400
	ds_read_b64_tr_b16 v[90:91], v0 offset:0x1c00
	ds_read_b64_tr_b16 v[92:93], v0 offset:0x2400
	ds_read_b64_tr_b16 v[94:95], v0 offset:0x2c00
	ds_read_b64_tr_b16 v[96:97], v0 offset:0x3400
	ds_read_b64_tr_b16 v[98:99], v0 offset:0x3c00
	s_waitcnt lgkmcnt(8)
	v_mfma_f32_32x32x16_bf16 v[48:63], v[2:5], v[100:103], v[48:63]
	v_mfma_f32_32x32x16_bf16 v[48:63], v[6:9], v[104:107], v[48:63]
	v_mfma_f32_32x32x16_bf16 v[48:63], v[10:13], v[108:111], v[48:63]
	v_mfma_f32_32x32x16_bf16 v[48:63], v[80:83], v[154:157], v[48:63]
	ds_read_b64_tr_b16 v[100:101], v0 offset:0x600
	ds_read_b64_tr_b16 v[102:103], v0 offset:0xe00
	ds_read_b64_tr_b16 v[104:105], v0 offset:0x1600
	ds_read_b64_tr_b16 v[106:107], v0 offset:0x1e00
	ds_read_b64_tr_b16 v[108:109], v0 offset:0x2600
	ds_read_b64_tr_b16 v[110:111], v0 offset:0x2e00
	ds_read_b64_tr_b16 v[154:155], v0 offset:0x3600
	ds_read_b64_tr_b16 v[156:157], v0 offset:0x3e00
	s_waitcnt lgkmcnt(8)
	v_mfma_f32_32x32x16_bf16 v[32:47], v[2:5], v[84:87], v[32:47]
	v_mfma_f32_32x32x16_bf16 v[32:47], v[6:9], v[88:91], v[32:47]
	v_mfma_f32_32x32x16_bf16 v[32:47], v[10:13], v[92:95], v[32:47]
	v_mfma_f32_32x32x16_bf16 v[32:47], v[80:83], v[96:99], v[32:47]
	s_waitcnt lgkmcnt(0)
	v_mfma_f32_32x32x16_bf16 v[16:31], v[2:5], v[100:103], v[16:31]
	v_mfma_f32_32x32x16_bf16 v[16:31], v[6:9], v[104:107], v[16:31]
	v_mfma_f32_32x32x16_bf16 v[16:31], v[10:13], v[108:111], v[16:31]
	v_mfma_f32_32x32x16_bf16 v[16:31], v[80:83], v[154:157], v[16:31]
	s_setprio 0
	v_cmp_lt_f32_e32 vcc, s81, v153
	s_and_saveexec_b64 s[0:1], s[38:39]
	s_cbranch_execz .LBB0_452

; #define LAS __attribute__((address_space(3)))
; __device__ __forceinline__ void qkt(f32x16& p0, f32x16& p1, const LAS char* K_buf, int r32, int hi, const bf16x8* qr) {
;     ...
;     for (int d0 = 0; d0 < 8; ++d0) { const LAS char* ap = kb[d0 & 3] + (d0 >> 2) * 128;
;         const bf16x8 b0 = *(const LAS bf16x8*)ap;
;         const bf16x8 b1 = *(const LAS bf16x8*)(ap + 32 * 256);
;         const bf16x8 qf = qr[d0];
;         p0 = __builtin_amdgcn_mfma_f32_32x32x16_bf16(b0, qf, p0, 0, 0, 0);
;         p1 = __builtin_amdgcn_mfma_f32_32x32x16_bf16(b1, qf, p1, 0, 0, 0); }
; template <bool SBK>
; __device__ __forceinline__ void attn_unit(const Args& a, int l, LAS char* lds, int b, int h8, int P0, int orow0, int nvalid) {
;     ...
;  for (int r = 0; r < 16; ++r) { const int c = (r & 3) + 8 * (r >> 2);
;                     float z = p0[r]; float lv = -(fmaxf(z, 0.f) + __builtin_amdgcn_logf(1.0f + __builtin_amdgcn_exp2f(-fabsf(z)))); if (needmask && (dq - c < 1)) lv = 0.f; l0[r] = lv;
;                     z = p1[r]; lv = -(fmaxf(z, 0.f) + __builtin_amdgcn_logf(1.0f + __builtin_amdgcn_exp2f(-fabsf(z)))); if (needmask && (dq - c - 32 < 1)) lv = 0.f; l1[r] = lv; }
.LBB0_512:
	s_lshl_b32 s7, s1, 14
	v_add_u32_e32 v0, s7, v165
	v_add_u32_e32 v10, v0, v166
	ds_read_b128 v[2:5], v10 offset:49152
	ds_read_b128 v[6:9], v10 offset:57344
	v_add_u32_e32 v11, v0, v167
	v_add_u32_e32 v12, v0, v168
	v_add_u32_e32 v0, v0, v169
	s_waitcnt lgkmcnt(0)
	s_setprio 1
	v_mfma_f32_32x32x16_bf16 v[96:111], v[2:5], v[112:115], 0
	s_cmp_lt_i32 s0, s30
	s_cselect_b64 s[28:29], -1, 0
	v_mfma_f32_32x32x16_bf16 v[80:95], v[6:9], v[112:115], 0
	ds_read_b128 v[2:5], v11 offset:49152
	ds_read_b128 v[6:9], v11 offset:57344
	s_waitcnt lgkmcnt(0)
	v_mfma_f32_32x32x16_bf16 v[96:111], v[2:5], v[116:119], v[96:111]
	v_mfma_f32_32x32x16_bf16 v[80:95], v[6:9], v[116:119], v[80:95]
	ds_read_b128 v[2:5], v12 offset:49152
	ds_read_b128 v[6:9], v12 offset:57344
	s_waitcnt lgkmcnt(0)
	v_mfma_f32_32x32x16_bf16 v[96:111], v[2:5], v[120:123], v[96:111]
	v_mfma_f32_32x32x16_bf16 v[80:95], v[6:9], v[120:123], v[80:95]
	ds_read_b128 v[2:5], v0 offset:49152
	ds_read_b128 v[6:9], v0 offset:57344
	s_waitcnt lgkmcnt(0)
	v_mfma_f32_32x32x16_bf16 v[96:111], v[2:5], v[124:127], v[96:111]
	v_mfma_f32_32x32x16_bf16 v[80:95], v[6:9], v[124:127], v[80:95]
	ds_read_b128 v[2:5], v10 offset:49280
	ds_read_b128 v[6:9], v10 offset:57472
	s_waitcnt lgkmcnt(0)
	v_mfma_f32_32x32x16_bf16 v[96:111], v[2:5], v[128:131], v[96:111]
	v_mfma_f32_32x32x16_bf16 v[80:95], v[6:9], v[128:131], v[80:95]
	ds_read_b128 v[2:5], v11 offset:49280
	ds_read_b128 v[6:9], v11 offset:57472
	s_waitcnt lgkmcnt(0)
	v_mfma_f32_32x32x16_bf16 v[96:111], v[2:5], v[132:135], v[96:111]
	v_mfma_f32_32x32x16_bf16 v[80:95], v[6:9], v[132:135], v[80:95]
	ds_read_b128 v[2:5], v12 offset:49280
	ds_read_b128 v[6:9], v12 offset:57472
	s_waitcnt lgkmcnt(0)
	v_mfma_f32_32x32x16_bf16 v[96:111], v[2:5], v[136:139], v[96:111]
	v_mfma_f32_32x32x16_bf16 v[80:95], v[6:9], v[136:139], v[80:95]
	ds_read_b128 v[2:5], v0 offset:49280
	ds_read_b128 v[6:9], v0 offset:57472
	v_or_b32_e32 v0, s0, v160
	s_waitcnt lgkmcnt(0)
	v_mfma_f32_32x32x16_bf16 v[96:111], v[2:5], v[140:143], v[96:111]
	v_sub_u32_e32 v3, v164, v0
	v_cmp_lt_i32_e32 vcc, 0, v3
	s_or_b64 vcc, s[28:29], vcc
	v_cmp_lt_i32_e64 s[0:1], 32, v3
	s_or_b64 s[40:41], s[28:29], s[0:1]
	v_cmp_lt_i32_e64 s[0:1], 1, v3
	s_or_b64 s[42:43], s[28:29], s[0:1]
	v_mfma_f32_32x32x16_bf16 v[80:95], v[6:9], v[140:143], v[80:95]
	s_setprio 0
	s_nop 3
	v_exp_f32_e64 v2, -|v96|
	v_exp_f32_e64 v5, -|v97|
	v_max_f32_e32 v0, v96, v96
	v_max_f32_e32 v0, 0, v0
	v_add_f32_e32 v2, 1.0, v2
	v_log_f32_e32 v2, v2
	v_add_f32_e32 v5, 1.0, v5
	s_nop 0
	v_exp_f32_e64 v4, -|v80|
	v_exp_f32_e64 v6, -|v81|
	v_add_f32_e32 v0, v0, v2
	v_cndmask_b32_e64 v2, 0, -v0, vcc
	v_add_f32_e32 v4, 1.0, v4
	v_log_f32_e32 v4, v4
	v_max_f32_e32 v0, v80, v80
	v_log_f32_e32 v5, v5
	v_max_f32_e32 v0, 0, v0
	v_add_f32_e32 v6, 1.0, v6
	v_add_f32_e32 v0, v0, v4
	v_max_f32_e32 v4, v97, v97
	v_log_f32_e32 v6, v6
	v_max_f32_e32 v4, 0, v4
	v_add_f32_e32 v4, v4, v5
	v_max_f32_e32 v5, v81, v81
	v_max_f32_e32 v5, 0, v5
	v_add_f32_e32 v5, v5, v6
	v_exp_f32_e64 v6, -|v98|
	v_exp_f32_e64 v7, -|v82|
	v_cmp_lt_i32_e64 s[0:1], 33, v3
	s_or_b64 s[44:45], s[28:29], s[0:1]
	v_add_f32_e32 v6, 1.0, v6
	v_log_f32_e32 v6, v6
	v_cndmask_b32_e64 v171, 0, -v5, s[44:45]
	v_max_f32_e32 v5, v98, v98
	v_add_f32_e32 v7, 1.0, v7
	v_max_f32_e32 v5, 0, v5
	v_cmp_lt_i32_e64 s[0:1], 2, v3
	v_log_f32_e32 v7, v7
	v_add_f32_e32 v5, v5, v6
	s_or_b64 s[46:47], s[28:29], s[0:1]
	v_cndmask_b32_e64 v6, 0, -v5, s[46:47]
	v_max_f32_e32 v5, v82, v82
	v_max_f32_e32 v5, 0, v5
	v_add_f32_e32 v5, v5, v7
	v_exp_f32_e64 v7, -|v99|
	v_cmp_lt_i32_e64 s[0:1], 34, v3
	s_or_b64 s[48:49], s[28:29], s[0:1]
	v_cndmask_b32_e64 v172, 0, -v5, s[48:49]
	v_add_f32_e32 v7, 1.0, v7
	v_log_f32_e32 v7, v7
	v_max_f32_e32 v5, v99, v99
	v_max_f32_e32 v5, 0, v5
	v_cmp_lt_i32_e64 s[0:1], 3, v3
	v_add_f32_e32 v5, v5, v7
	v_exp_f32_e64 v7, -|v83|
	s_or_b64 s[52:53], s[28:29], s[0:1]
	v_cndmask_b32_e64 v8, 0, -v5, s[52:53]
	v_max_f32_e32 v5, v83, v83
	v_add_f32_e32 v7, 1.0, v7
	v_log_f32_e32 v7, v7
	v_max_f32_e32 v5, 0, v5
	v_cmp_lt_i32_e64 s[0:1], 35, v3
	s_or_b64 s[56:57], s[28:29], s[0:1]
	v_add_f32_e32 v5, v5, v7
	v_exp_f32_e64 v7, -|v100|
	v_cndmask_b32_e64 v175, 0, -v5, s[56:57]
	v_max_f32_e32 v5, v100, v100
	v_max_f32_e32 v5, 0, v5
	v_add_f32_e32 v7, 1.0, v7
	v_log_f32_e32 v7, v7
	v_cmp_lt_i32_e64 s[0:1], 8, v3
	s_or_b64 s[50:51], s[28:29], s[0:1]
	v_cmp_lt_i32_e64 s[0:1], 40, v3
	v_add_f32_e32 v5, v5, v7
	v_exp_f32_e64 v7, -|v84|
	v_cndmask_b32_e64 v173, 0, -v5, s[50:51]
	v_max_f32_e32 v5, v84, v84
	v_max_f32_e32 v5, 0, v5
	v_add_f32_e32 v7, 1.0, v7
	v_log_f32_e32 v7, v7
	s_or_b64 s[54:55], s[28:29], s[0:1]
	v_cmp_lt_i32_e64 s[0:1], 9, v3
	s_or_b64 s[58:59], s[28:29], s[0:1]
	v_add_f32_e32 v5, v5, v7
	v_exp_f32_e64 v7, -|v101|
	v_cndmask_b32_e64 v174, 0, -v5, s[54:55]
	v_max_f32_e32 v5, v101, v101
	v_max_f32_e32 v5, 0, v5
	v_add_f32_e32 v7, 1.0, v7
	v_log_f32_e32 v7, v7
	v_cmp_lt_i32_e64 s[0:1], 41, v3
	s_or_b64 s[60:61], s[28:29], s[0:1]
	v_cmp_lt_i32_e64 s[0:1], 10, v3
	v_add_f32_e32 v5, v5, v7
	v_exp_f32_e64 v7, -|v85|
	v_cndmask_b32_e64 v176, 0, -v5, s[58:59]
	v_max_f32_e32 v5, v85, v85
	v_max_f32_e32 v5, 0, v5
	v_add_f32_e32 v7, 1.0, v7
	v_log_f32_e32 v7, v7
	s_or_b64 s[62:63], s[28:29], s[0:1]
	v_cmp_lt_i32_e64 s[0:1], 42, v3
	s_or_b64 s[64:65], s[28:29], s[0:1]
	v_add_f32_e32 v5, v5, v7
	v_exp_f32_e64 v7, -|v102|
	v_cndmask_b32_e64 v177, 0, -v5, s[60:61]
	v_max_f32_e32 v5, v102, v102
	v_max_f32_e32 v5, 0, v5
	v_add_f32_e32 v7, 1.0, v7
	v_log_f32_e32 v7, v7
	v_cmp_lt_i32_e64 s[0:1], 11, v3
	s_or_b64 s[68:69], s[28:29], s[0:1]
	v_cmp_lt_i32_e64 s[0:1], 43, v3
	v_add_f32_e32 v5, v5, v7
; __device__ __forceinline__ float pair_other(float x, int hi) { auto rr = __builtin_amdgcn_permlane32_swap(__float_as_uint(x), __float_as_uint(x), false, false); return __uint_as_float(hi ? rr[0] : rr[1]); }
; template <bool SBK>
; __device__ __forceinline__ void attn_unit(const Args& a, int l, LAS char* lds, int b, int h8, int P0, int orow0, int nvalid) {
;     ...
;                     float z = p0[r]; float lv = -(fmaxf(z, 0.f) + __builtin_amdgcn_logf(1.0f + __builtin_amdgcn_exp2f(-fabsf(z)))); if (needmask && (dq - c < 1)) lv = 0.f; l0[r] = lv;
;                     z = p1[r]; lv = -(fmaxf(z, 0.f) + __builtin_amdgcn_logf(1.0f + __builtin_amdgcn_exp2f(-fabsf(z)))); if (needmask && (dq - c - 32 < 1)) lv = 0.f; l1[r] = lv; }
;                 float gs[8], pg[8], aft[8];
; #pragma unroll
;  for (int i = 0; i < 4; ++i) { gs[i] = (l0[4 * i] + l0[4 * i + 1]) + (l0[4 * i + 2] + l0[4 * i + 3]); gs[4 + i] = (l1[4 * i] + l1[4 * i + 1]) + (l1[4 * i + 2] + l1[4 * i + 3]); }
; #pragma unroll
;  for (int i = 0; i < 8; ++i) pg[i] = pair_other(gs[i], hi);
	v_exp_f32_e64 v7, -|v86|
	v_cndmask_b32_e64 v178, 0, -v5, s[62:63]
	v_max_f32_e32 v5, v86, v86
	v_max_f32_e32 v5, 0, v5
	v_add_f32_e32 v7, 1.0, v7
	v_log_f32_e32 v7, v7
	s_or_b64 s[72:73], s[28:29], s[0:1]
	v_cmp_lt_i32_e64 s[0:1], 16, v3
	s_or_b64 s[66:67], s[28:29], s[0:1]
	v_add_f32_e32 v5, v5, v7
	v_exp_f32_e64 v7, -|v103|
	v_cndmask_b32_e64 v179, 0, -v5, s[64:65]
	v_max_f32_e32 v5, v103, v103
	v_max_f32_e32 v5, 0, v5
	v_add_f32_e32 v7, 1.0, v7
	v_log_f32_e32 v7, v7
	v_cmp_lt_i32_e64 s[0:1], 48, v3
	s_or_b64 s[70:71], s[28:29], s[0:1]
	v_cmp_lt_i32_e64 s[0:1], 17, v3
	v_add_f32_e32 v5, v5, v7
	v_exp_f32_e64 v7, -|v87|
	v_cndmask_b32_e64 v181, 0, -v5, s[68:69]
	v_max_f32_e32 v5, v87, v87
	v_max_f32_e32 v5, 0, v5
	v_add_f32_e32 v7, 1.0, v7
	v_log_f32_e32 v7, v7
	s_or_b64 s[74:75], s[28:29], s[0:1]
	v_cmp_lt_i32_e64 s[0:1], 49, v3
	s_or_b64 s[76:77], s[28:29], s[0:1]
	v_add_f32_e32 v5, v5, v7
	v_exp_f32_e64 v7, -|v104|
	v_cndmask_b32_e64 v182, 0, -v5, s[72:73]
	v_max_f32_e32 v5, v104, v104
	v_max_f32_e32 v5, 0, v5
	v_add_f32_e32 v7, 1.0, v7
	v_log_f32_e32 v7, v7
	v_cmp_lt_i32_e64 s[0:1], 18, v3
	s_or_b64 s[78:79], s[28:29], s[0:1]
	v_cmp_lt_i32_e64 s[0:1], 50, v3
	v_add_f32_e32 v5, v5, v7
	v_exp_f32_e64 v7, -|v88|
	v_cndmask_b32_e64 v180, 0, -v5, s[66:67]
	v_max_f32_e32 v5, v88, v88
	v_max_f32_e32 v5, 0, v5
	v_add_f32_e32 v7, 1.0, v7
	v_log_f32_e32 v7, v7
	s_or_b64 s[80:81], s[28:29], s[0:1]
	v_cmp_lt_i32_e64 s[0:1], 19, v3
	s_or_b64 s[84:85], s[28:29], s[0:1]
	v_add_f32_e32 v5, v5, v7
	v_exp_f32_e64 v7, -|v105|
	v_cndmask_b32_e64 v10, 0, -v5, s[70:71]
	v_max_f32_e32 v5, v105, v105
	v_max_f32_e32 v5, 0, v5
	v_add_f32_e32 v7, 1.0, v7
	v_log_f32_e32 v7, v7
	v_cmp_lt_i32_e64 s[0:1], 51, v3
	s_or_b64 s[88:89], s[28:29], s[0:1]
	v_cmp_lt_i32_e64 s[0:1], 24, v3
	v_add_f32_e32 v5, v5, v7
	v_exp_f32_e64 v7, -|v89|
	v_cndmask_b32_e64 v183, 0, -v5, s[74:75]
	v_max_f32_e32 v5, v89, v89
	v_max_f32_e32 v5, 0, v5
	v_add_f32_e32 v7, 1.0, v7
	v_log_f32_e32 v7, v7
	s_or_b64 s[82:83], s[28:29], s[0:1]
	v_cmp_lt_i32_e64 s[0:1], 56, v3
	s_or_b64 s[86:87], s[28:29], s[0:1]
	v_add_f32_e32 v5, v5, v7
	v_exp_f32_e64 v7, -|v106|
	v_cndmask_b32_e64 v12, 0, -v5, s[76:77]
	v_max_f32_e32 v5, v106, v106
	v_max_f32_e32 v5, 0, v5
	v_add_f32_e32 v7, 1.0, v7
	v_log_f32_e32 v7, v7
	v_cmp_lt_i32_e64 s[0:1], 25, v3
	s_or_b64 s[90:91], s[28:29], s[0:1]
	v_cmp_lt_i32_e64 s[0:1], 57, v3
	v_add_f32_e32 v5, v5, v7
	v_exp_f32_e64 v7, -|v90|
	v_cndmask_b32_e64 v184, 0, -v5, s[78:79]
	v_max_f32_e32 v5, v90, v90
	v_max_f32_e32 v5, 0, v5
	v_add_f32_e32 v7, 1.0, v7
	v_log_f32_e32 v7, v7
	s_or_b64 s[92:93], s[28:29], s[0:1]
	v_cmp_lt_i32_e64 s[0:1], 26, v3
	s_or_b64 s[94:95], s[28:29], s[0:1]
	v_add_f32_e32 v5, v5, v7
	v_exp_f32_e64 v7, -|v107|
	v_cndmask_b32_e64 v185, 0, -v5, s[80:81]
	v_max_f32_e32 v5, v107, v107
	v_max_f32_e32 v5, 0, v5
	v_add_f32_e32 v7, 1.0, v7
	v_log_f32_e32 v7, v7
	v_cmp_lt_i32_e64 s[0:1], 58, v3
	s_or_b64 s[96:97], s[28:29], s[0:1]
	v_cmp_lt_i32_e64 s[0:1], 27, v3
	v_add_f32_e32 v5, v5, v7
	v_exp_f32_e64 v7, -|v91|
	v_cndmask_b32_e64 v194, 0, -v5, s[84:85]
	v_max_f32_e32 v5, v91, v91
	v_max_f32_e32 v5, 0, v5
	v_add_f32_e32 v7, 1.0, v7
	v_log_f32_e32 v7, v7
	s_or_b64 s[0:1], s[28:29], s[0:1]
	v_cmp_lt_i32_e64 s[4:5], 59, v3
	v_cndmask_b32_e64 v0, 0, -v0, s[40:41]
	v_add_f32_e32 v5, v5, v7
	v_exp_f32_e64 v7, -|v108|
	v_cndmask_b32_e64 v196, 0, -v5, s[88:89]
	v_max_f32_e32 v5, v108, v108
	v_max_f32_e32 v5, 0, v5
	v_add_f32_e32 v7, 1.0, v7
	v_log_f32_e32 v7, v7
	s_or_b64 s[4:5], s[28:29], s[4:5]
	v_add_f32_e32 v3, v0, v171
	v_add_f32_e32 v9, v184, v194
	v_add_f32_e32 v5, v5, v7
	v_exp_f32_e64 v7, -|v92|
	v_cndmask_b32_e64 v14, 0, -v5, s[82:83]
	v_max_f32_e32 v5, v92, v92
	v_max_f32_e32 v5, 0, v5
	v_add_f32_e32 v7, 1.0, v7
	v_log_f32_e32 v7, v7
	v_add_f32_e32 v186, v185, v196
	v_cndmask_b32_e64 v4, 0, -v4, s[42:43]
	v_add_f32_e32 v5, v5, v7
	v_exp_f32_e64 v7, -|v109|
	v_cndmask_b32_e64 v195, 0, -v5, s[86:87]
	v_max_f32_e32 v5, v109, v109
	v_max_f32_e32 v5, 0, v5
	v_add_f32_e32 v7, 1.0, v7
	v_log_f32_e32 v7, v7
	s_nop 0
	v_add_f32_e32 v5, v5, v7
	v_exp_f32_e64 v7, -|v93|
	v_cndmask_b32_e64 v154, 0, -v5, s[90:91]
	v_max_f32_e32 v5, v93, v93
	v_max_f32_e32 v5, 0, v5
	v_add_f32_e32 v7, 1.0, v7
	v_log_f32_e32 v7, v7
	s_nop 0
	v_add_f32_e32 v5, v5, v7
	v_exp_f32_e64 v7, -|v110|
	v_cndmask_b32_e64 v197, 0, -v5, s[92:93]
	v_max_f32_e32 v5, v110, v110
	v_max_f32_e32 v5, 0, v5
	v_add_f32_e32 v7, 1.0, v7
	v_log_f32_e32 v7, v7
	v_add_f32_e32 v11, v195, v197
	v_add_f32_e32 v5, v5, v7
	v_exp_f32_e64 v7, -|v94|
	v_cndmask_b32_e64 v156, 0, -v5, s[94:95]
	v_max_f32_e32 v5, v94, v94
	v_max_f32_e32 v5, 0, v5
	v_add_f32_e32 v7, 1.0, v7
	v_log_f32_e32 v7, v7
	s_nop 0
	v_add_f32_e32 v5, v5, v7
	v_exp_f32_e64 v7, -|v111|
	v_cndmask_b32_e64 v190, 0, -v5, s[96:97]
	v_max_f32_e32 v5, v111, v111
	v_max_f32_e32 v5, 0, v5
	v_add_f32_e32 v7, 1.0, v7
	v_log_f32_e32 v7, v7
	s_nop 0
	v_add_f32_e32 v5, v5, v7
	v_exp_f32_e64 v7, -|v95|
	v_cndmask_b32_e64 v158, 0, -v5, s[0:1]
	v_max_f32_e32 v5, v95, v95
	v_max_f32_e32 v5, 0, v5
	v_add_f32_e32 v7, 1.0, v7
	v_log_f32_e32 v7, v7
	s_nop 0
	v_add_f32_e32 v5, v5, v7
	v_cndmask_b32_e64 v191, 0, -v5, s[4:5]
	v_add_f32_e32 v5, v172, v175
	v_add_f32_e32 v15, v3, v5
	v_add_f32_e32 v3, v173, v176
	v_add_f32_e32 v5, v178, v181
	v_add_f32_e32 v3, v3, v5
	v_add_f32_e32 v5, v174, v177
	v_add_f32_e32 v7, v179, v182
	v_add_f32_e32 v7, v5, v7
	v_add_f32_e32 v5, v180, v183
	v_add_f32_e32 v192, v5, v9
	v_add_f32_e32 v13, v190, v191
	v_mov_b32_e32 v5, v3
	v_mov_b32_e32 v9, v3
	s_nop 1
	v_permlane32_swap_b32_e32 v5, v9
	v_pk_add_f32 v[188:189], v[10:11], v[12:13]
; __device__ __forceinline__ float pair_other(float x, int hi) { auto rr = __builtin_amdgcn_permlane32_swap(__float_as_uint(x), __float_as_uint(x), false, false); return __uint_as_float(hi ? rr[0] : rr[1]); }
; template <bool SBK>
; __device__ __forceinline__ void attn_unit(const Args& a, int l, LAS char* lds, int b, int h8, int P0, int orow0, int nvalid) {
;     ...
;                 float gs[8], pg[8], aft[8];
; #pragma unroll
;  for (int i = 0; i < 4; ++i) { gs[i] = (l0[4 * i] + l0[4 * i + 1]) + (l0[4 * i + 2] + l0[4 * i + 3]); gs[4 + i] = (l1[4 * i] + l1[4 * i + 1]) + (l1[4 * i + 2] + l1[4 * i + 3]); }
; #pragma unroll
;  for (int i = 0; i < 8; ++i) pg[i] = pair_other(gs[i], hi);
;                 float run = R;
; #pragma unroll
;  for (int i = 7; i >= 0; --i) { aft[i] = run + (hi ? 0.f : pg[i]); run += gs[i] + pg[i]; }
;                 R = run;
; #pragma unroll
;  for (int i = 0; i < 4; ++i) { float c0 = aft[i], c1 = aft[4 + i];
; #pragma unroll
;  for (int e = 3; e >= 0; --e) { const int r = 4 * i + e; const int c = (r & 3) + 8 * (r >> 2);
;                         c0 += l0[r]; float av = __builtin_amdgcn_exp2f(p0[r] + c0); if (needmask && (dq - c < 1)) av = 0.f; p0[r] = av;
;                         c1 += l1[r]; av = __builtin_amdgcn_exp2f(p1[r] + c1); if (needmask && (dq - c - 32 < 1)) av = 0.f; p1[r] = av; } }
	v_cndmask_b32_e64 v5, v5, v9, s[36:37]
	v_mov_b32_e32 v9, v192
	v_mov_b32_e32 v152, v192
	v_mov_b32_e32 v11, v189
	v_mov_b32_e32 v13, v189
	v_permlane32_swap_b32_e32 v9, v152
	s_nop 0
	v_permlane32_swap_b32_e32 v11, v13
	v_cndmask_b32_e64 v193, v9, v152, s[36:37]
	v_mov_b32_e32 v9, v15
	v_mov_b32_e32 v152, v15
	v_cndmask_b32_e64 v187, v11, v13, s[36:37]
	s_nop 0
	v_permlane32_swap_b32_e32 v9, v152
	v_pk_add_f32 v[188:189], v[188:189], v[186:187]
	v_cndmask_b32_e64 v155, v9, v152, s[36:37]
	v_mov_b32_e32 v9, v7
	v_mov_b32_e32 v152, v7
	v_mov_b32_e32 v11, v188
	v_mov_b32_e32 v13, v188
	v_permlane32_swap_b32_e32 v9, v152
	s_nop 0
	v_permlane32_swap_b32_e32 v11, v13
	v_cndmask_b32_e64 v9, v9, v152, s[36:37]
	v_cndmask_b32_e64 v152, v11, v13, s[36:37]
	v_cndmask_b32_e64 v11, 0, v187, s[36:37]
	v_add_f32_e32 v11, v153, v11
	v_cndmask_b32_e64 v13, 0, v152, s[36:37]
	v_pk_add_f32 v[152:153], v[188:189], v[152:153]
	v_add_f32_e32 v157, v7, v9
	v_add_f32_e32 v13, v13, v153
	v_pk_add_f32 v[152:153], v[152:153], v[152:153] op_sel:[0,1] op_sel_hi:[1,0]
	v_pk_add_f32 v[186:187], v[14:15], v[154:155]
	v_cndmask_b32_e64 v153, 0, v9, s[36:37]
	v_mov_b32_e32 v159, v152
	v_add_f32_e32 v188, v153, v152
	v_pk_add_f32 v[152:153], v[156:157], v[158:159]
	v_cndmask_b32_e64 v7, 0, v155, s[36:37]
	v_pk_add_f32 v[186:187], v[186:187], v[152:153]
	v_add_f32_e32 v13, v196, v13
	v_mov_b32_e32 v9, v186
	v_mov_b32_e32 v15, v186
	s_nop 1
	v_permlane32_swap_b32_e32 v9, v15
	v_cndmask_b32_e64 v9, v9, v15, s[36:37]
	v_add_f32_e32 v15, v7, v153
	v_cndmask_b32_e64 v7, 0, v9, s[36:37]
	v_add_f32_e32 v155, v7, v187
	v_add_f32_e32 v7, v186, v9
	v_add_f32_e32 v9, v7, v187
	v_cndmask_b32_e64 v7, 0, v193, s[36:37]
	v_add_f32_e32 v157, v7, v9
	v_add_f32_e32 v7, v192, v193
	v_pk_add_f32 v[186:187], v[6:7], v[8:9]
	v_add_f32_e32 v9, v175, v15
	v_add_f32_e32 v15, v83, v9
	v_add_f32_e32 v9, v172, v9
	v_pk_add_f32 v[152:153], v[2:3], v[4:5]
	v_add_f32_e32 v82, v82, v9
	v_add_f32_e32 v9, v171, v9
	v_add_f32_e32 v91, v91, v13
	v_add_f32_e32 v13, v185, v13
	v_pk_add_f32 v[152:153], v[152:153], v[186:187]
	v_add_f32_e32 v81, v81, v9
	v_add_f32_e32 v0, v0, v9
	v_add_f32_e32 v9, v182, v188
	v_add_f32_e32 v12, v12, v13
	v_cndmask_b32_e64 v159, 0, v5, s[36:37]
	v_mov_b32_e32 v3, v152
	v_mov_b32_e32 v5, v152
	v_add_f32_e32 v0, v80, v0
	v_add_f32_e32 v80, v87, v9
	v_add_f32_e32 v9, v179, v9
	v_add_f32_e32 v90, v90, v13
	v_add_f32_e32 v13, v89, v12
	v_permlane32_swap_b32_e32 v3, v5
	v_add_f32_e32 v86, v86, v9
	v_add_f32_e32 v9, v177, v9
	v_exp_f32_e32 v13, v13
	v_cndmask_b32_e64 v3, v3, v5, s[36:37]
	v_add_f32_e32 v85, v85, v9
	v_add_f32_e32 v9, v174, v9
	v_add_f32_e32 v10, v10, v12
	v_cndmask_b32_e64 v7, 0, v3, s[36:37]
	v_add_f32_e32 v9, v84, v9
	v_add_f32_e32 v10, v88, v10
	v_add_f32_e32 v7, v7, v153
	v_exp_f32_e32 v9, v9
	v_exp_f32_e32 v10, v10
	v_add_f32_e32 v11, v191, v11
	v_add_f32_e32 v7, v8, v7
	v_cndmask_b32_e64 v89, 0, v13, s[76:77]
	v_add_f32_e32 v13, v95, v11
	v_add_f32_e32 v6, v6, v7
	v_exp_f32_e32 v13, v13
	v_add_f32_e32 v5, v159, v187
	v_add_f32_e32 v4, v4, v6
	v_add_f32_e32 v8, v99, v7
	v_add_f32_e32 v7, v98, v6
	v_add_f32_e32 v6, v97, v4
	v_add_f32_e32 v2, v2, v4
	v_add_f32_e32 v4, v181, v5
	v_cndmask_b32_e64 v84, 0, v9, s[54:55]
	v_add_f32_e32 v9, v194, v157
	v_cndmask_b32_e64 v88, 0, v10, s[70:71]
	v_add_f32_e32 v10, v158, v155
	v_add_f32_e32 v2, v96, v2
	v_add_f32_e32 v5, v103, v4
	v_add_f32_e32 v4, v178, v4
	v_add_f32_e32 v96, v107, v9
	v_add_f32_e32 v9, v184, v9
	v_add_f32_e32 v12, v111, v10
	v_add_f32_e32 v10, v156, v10
	v_add_f32_e32 v83, v102, v4
	v_add_f32_e32 v4, v176, v4
	v_add_f32_e32 v97, v106, v9
	v_add_f32_e32 v9, v183, v9
	v_cndmask_b32_e64 v95, 0, v13, s[4:5]
	v_add_f32_e32 v13, v110, v10
	v_add_f32_e32 v11, v190, v11
	v_add_f32_e32 v10, v154, v10
	v_add_f32_e32 v87, v101, v4
	v_add_f32_e32 v4, v173, v4
	v_add_f32_e32 v98, v105, v9
	v_add_f32_e32 v9, v180, v9
	v_add_f32_e32 v94, v94, v11
	v_add_f32_e32 v99, v109, v10
	v_add_f32_e32 v11, v197, v11
	v_add_f32_e32 v10, v14, v10
	v_add_f32_e32 v4, v100, v4
	v_add_f32_e32 v9, v104, v9
	v_add_f32_e32 v93, v93, v11
	v_add_f32_e32 v10, v108, v10
	v_add_f32_e32 v11, v195, v11
	v_exp_f32_e32 v8, v8
	v_exp_f32_e32 v7, v7
	v_exp_f32_e32 v82, v82
	v_exp_f32_e32 v6, v6
	v_exp_f32_e32 v81, v81
	v_exp_f32_e32 v2, v2
	v_exp_f32_e32 v0, v0
	v_exp_f32_e32 v5, v5
	v_exp_f32_e32 v80, v80
	v_exp_f32_e32 v83, v83
	v_exp_f32_e32 v85, v85
	v_exp_f32_e32 v4, v4
	v_exp_f32_e32 v9, v9
	v_exp_f32_e32 v12, v12
	v_exp_f32_e32 v13, v13
	v_exp_f32_e32 v10, v10
	v_add_f32_e32 v11, v92, v11
	v_exp_f32_e32 v15, v15
	v_exp_f32_e32 v86, v86
	v_exp_f32_e32 v87, v87
	v_exp_f32_e32 v96, v96
	v_exp_f32_e32 v91, v91
	v_exp_f32_e32 v97, v97
	v_exp_f32_e32 v90, v90
	v_exp_f32_e32 v98, v98
	v_exp_f32_e32 v94, v94
	v_exp_f32_e32 v99, v99
	v_exp_f32_e32 v93, v93
	v_exp_f32_e32 v11, v11
	v_add_f32_e32 v3, v152, v3
	v_cndmask_b32_e64 v8, 0, v8, s[52:53]
; #define PV_RD(d0, F) do { constexpr int b_ = v_rd_off(d0, 0, 0); \
;         TRRD(F[0], b_); TRRD(F[1], b_ + 2048); TRRD(F[2], b_ + 4096); TRRD(F[3], b_ + 6144); TRRD(F[4], b_ + 8192); TRRD(F[5], b_ + 10240); TRRD(F[6], b_ + 12288); TRRD(F[7], b_ + 14336); } while (0)
; #define LGK(n) do { asm volatile("s_waitcnt lgkmcnt(" #n ")" ::: "memory"); __builtin_amdgcn_sched_barrier(0); } while (0)
; __device__ __forceinline__ void pv_tile(f32x16* o, int vb0  , bf16x8 pa0, bf16x8 pa1, bf16x8 pa2, bf16x8 pa3) {
;     ...
;     s16x4 fa[8], fb[8];
;     PV_RD(0, fa); PV_RD(1, fb);
;     LGK(8); PV_MM(0, fa); __builtin_amdgcn_sched_barrier(0);
;     PV_RD(2, fa);
;     LGK(8); PV_MM(1, fb); __builtin_amdgcn_sched_barrier(0);
;     PV_RD(3, fb);
;     LGK(8); PV_MM(2, fa); __builtin_amdgcn_sched_barrier(0);
;     LGK(0); PV_MM(3, fb);
;     ...
; }
; template <bool SBK>
; __device__ __forceinline__ void attn_unit(const Args& a, int l, LAS char* lds, int b, int h8, int P0, int orow0, int nvalid) {
;     ...
;             PK4(p0, 0, pa0); PK4(p0, 8, pa1); PK4(p1, 0, pa2); PK4(p1, 8, pa3);
;             pv_tile(o, vb0 + vb * SHM_V, pa0, pa1, pa2, pa3);
;         }
;         if constexpr (SBK) { const bool alive = __any(R > SB_EXIT); if (lane == 0) flag[(t & 1) * 8 + wid] = alive ? 1u : 0u; }
	v_cndmask_b32_e64 v7, 0, v7, s[46:47]
	v_cndmask_b32_e64 v82, 0, v82, s[48:49]
	v_cndmask_b32_e64 v6, 0, v6, s[42:43]
	v_cndmask_b32_e64 v81, 0, v81, s[44:45]
	v_cndmask_b32_e32 v2, 0, v2, vcc
	v_cndmask_b32_e64 v0, 0, v0, s[40:41]
	v_cndmask_b32_e64 v5, 0, v5, s[68:69]
	v_cndmask_b32_e64 v80, 0, v80, s[72:73]
	v_cndmask_b32_e64 v83, 0, v83, s[62:63]
	v_cndmask_b32_e64 v85, 0, v85, s[60:61]
	v_cndmask_b32_e64 v4, 0, v4, s[50:51]
	v_cndmask_b32_e64 v9, 0, v9, s[66:67]
	v_cndmask_b32_e64 v12, 0, v12, s[0:1]
	v_cndmask_b32_e64 v13, 0, v13, s[94:95]
	v_cndmask_b32_e64 v10, 0, v10, s[82:83]
	v_cndmask_b32_e64 v15, 0, v15, s[56:57]
	v_cndmask_b32_e64 v86, 0, v86, s[64:65]
	v_cndmask_b32_e64 v87, 0, v87, s[58:59]
	v_cndmask_b32_e64 v96, 0, v96, s[84:85]
	v_cndmask_b32_e64 v91, 0, v91, s[88:89]
	v_cndmask_b32_e64 v97, 0, v97, s[78:79]
	v_cndmask_b32_e64 v90, 0, v90, s[80:81]
	v_cndmask_b32_e64 v98, 0, v98, s[74:75]
	v_cndmask_b32_e64 v94, 0, v94, s[96:97]
	v_cndmask_b32_e64 v99, 0, v99, s[90:91]
	v_cndmask_b32_e64 v93, 0, v93, s[92:93]
	v_cndmask_b32_e64 v14, 0, v11, s[86:87]
	v_add_f32_e32 v153, v3, v153
	v_cvt_pk_bf16_f32 v2, v2, v6
	v_cvt_pk_bf16_f32 v3, v7, v8
	v_cvt_pk_bf16_f32 v4, v4, v87
	v_cvt_pk_bf16_f32 v5, v83, v5
	v_cvt_pk_bf16_f32 v6, v9, v98
	v_cvt_pk_bf16_f32 v7, v97, v96
	v_cvt_pk_bf16_f32 v8, v10, v99
	v_cvt_pk_bf16_f32 v9, v13, v12
	v_cvt_pk_bf16_f32 v10, v0, v81
	v_cvt_pk_bf16_f32 v11, v82, v15
	v_cvt_pk_bf16_f32 v12, v84, v85
	v_cvt_pk_bf16_f32 v13, v86, v80
	v_cvt_pk_bf16_f32 v80, v88, v89
	v_cvt_pk_bf16_f32 v81, v90, v91
	v_cvt_pk_bf16_f32 v82, v14, v93
	v_cvt_pk_bf16_f32 v83, v94, v95
	v_add_u32_e32 v0, s7, v170
	ds_read_b64_tr_b16 v[84:85], v0 offset:0
	ds_read_b64_tr_b16 v[86:87], v0 offset:0x800
	ds_read_b64_tr_b16 v[88:89], v0 offset:0x1000
	ds_read_b64_tr_b16 v[90:91], v0 offset:0x1800
	ds_read_b64_tr_b16 v[92:93], v0 offset:0x2000
	ds_read_b64_tr_b16 v[94:95], v0 offset:0x2800
	ds_read_b64_tr_b16 v[96:97], v0 offset:0x3000
	ds_read_b64_tr_b16 v[98:99], v0 offset:0x3800
	ds_read_b64_tr_b16 v[100:101], v0 offset:0x200
	ds_read_b64_tr_b16 v[102:103], v0 offset:0xa00
	ds_read_b64_tr_b16 v[104:105], v0 offset:0x1200
	ds_read_b64_tr_b16 v[106:107], v0 offset:0x1a00
	ds_read_b64_tr_b16 v[108:109], v0 offset:0x2200
	ds_read_b64_tr_b16 v[110:111], v0 offset:0x2a00
	ds_read_b64_tr_b16 v[154:155], v0 offset:0x3200
	ds_read_b64_tr_b16 v[156:157], v0 offset:0x3a00
	s_waitcnt lgkmcnt(8)
	v_readlane_b32 s62, v255, 9
	v_readlane_b32 s63, v255, 10
	s_movk_i32 s61, 0x100
	v_readlane_b32 s60, v255, 8
	s_mov_b32 s81, 0xc2200000
	s_movk_i32 s80, 0x3000
	s_mov_b32 s82, 0xc2700000
	v_permlane32_swap_b32_e32 v2, v4
	v_permlane32_swap_b32_e32 v3, v5
	v_permlane32_swap_b32_e32 v6, v8
	v_permlane32_swap_b32_e32 v7, v9
	v_permlane32_swap_b32_e32 v10, v12
	v_permlane32_swap_b32_e32 v11, v13
	v_permlane32_swap_b32_e32 v80, v82
	v_permlane32_swap_b32_e32 v81, v83
	s_setprio 1
	v_mfma_f32_32x32x16_bf16 v[64:79], v[2:5], v[84:87], v[64:79]
	v_mfma_f32_32x32x16_bf16 v[64:79], v[6:9], v[88:91], v[64:79]
	v_mfma_f32_32x32x16_bf16 v[64:79], v[10:13], v[92:95], v[64:79]
	v_mfma_f32_32x32x16_bf16 v[64:79], v[80:83], v[96:99], v[64:79]
	ds_read_b64_tr_b16 v[84:85], v0 offset:0x400
	ds_read_b64_tr_b16 v[86:87], v0 offset:0xc00
	ds_read_b64_tr_b16 v[88:89], v0 offset:0x1400
	ds_read_b64_tr_b16 v[90:91], v0 offset:0x1c00
	ds_read_b64_tr_b16 v[92:93], v0 offset:0x2400
	ds_read_b64_tr_b16 v[94:95], v0 offset:0x2c00
	ds_read_b64_tr_b16 v[96:97], v0 offset:0x3400
	ds_read_b64_tr_b16 v[98:99], v0 offset:0x3c00
	s_waitcnt lgkmcnt(8)
	v_mfma_f32_32x32x16_bf16 v[48:63], v[2:5], v[100:103], v[48:63]
	v_mfma_f32_32x32x16_bf16 v[48:63], v[6:9], v[104:107], v[48:63]
	v_mfma_f32_32x32x16_bf16 v[48:63], v[10:13], v[108:111], v[48:63]
	v_mfma_f32_32x32x16_bf16 v[48:63], v[80:83], v[154:157], v[48:63]
	ds_read_b64_tr_b16 v[100:101], v0 offset:0x600
	ds_read_b64_tr_b16 v[102:103], v0 offset:0xe00
	ds_read_b64_tr_b16 v[104:105], v0 offset:0x1600
	ds_read_b64_tr_b16 v[106:107], v0 offset:0x1e00
	ds_read_b64_tr_b16 v[108:109], v0 offset:0x2600
	ds_read_b64_tr_b16 v[110:111], v0 offset:0x2e00
	ds_read_b64_tr_b16 v[154:155], v0 offset:0x3600
	ds_read_b64_tr_b16 v[156:157], v0 offset:0x3e00
	s_waitcnt lgkmcnt(8)
	v_mfma_f32_32x32x16_bf16 v[32:47], v[2:5], v[84:87], v[32:47]
	v_mfma_f32_32x32x16_bf16 v[32:47], v[6:9], v[88:91], v[32:47]
	v_mfma_f32_32x32x16_bf16 v[32:47], v[10:13], v[92:95], v[32:47]
	v_mfma_f32_32x32x16_bf16 v[32:47], v[80:83], v[96:99], v[32:47]
	s_waitcnt lgkmcnt(0)
	v_mfma_f32_32x32x16_bf16 v[16:31], v[2:5], v[100:103], v[16:31]
	v_mfma_f32_32x32x16_bf16 v[16:31], v[6:9], v[104:107], v[16:31]
	v_mfma_f32_32x32x16_bf16 v[16:31], v[10:13], v[108:111], v[16:31]
	v_mfma_f32_32x32x16_bf16 v[16:31], v[80:83], v[154:157], v[16:31]
	s_setprio 0
	v_cmp_lt_f32_e32 vcc, s81, v153
	s_and_saveexec_b64 s[0:1], s[38:39]
	s_cbranch_execz .LBB0_506

; #define LAS __attribute__((address_space(3)))
; __device__ __forceinline__ void qkt(f32x16& p0, f32x16& p1, const LAS char* K_buf, int r32, int hi, const bf16x8* qr) {
;     p0 = f32x16{}; p1 = f32x16{};
;     const LAS char* kb[4];
; #pragma unroll
;     for (int dd = 0; dd < 4; ++dd) kb[dd] = K_buf + KSWZ(r32, (dd * 16 + hi * 8) * 2);
; #pragma unroll
;     for (int d0 = 0; d0 < 8; ++d0) { const LAS char* ap = kb[d0 & 3] + (d0 >> 2) * 128;
;         const bf16x8 b0 = *(const LAS bf16x8*)ap;
;         const bf16x8 b1 = *(const LAS bf16x8*)(ap + 32 * 256);
;         const bf16x8 qf = qr[d0];
;         p0 = __builtin_amdgcn_mfma_f32_32x32x16_bf16(b0, qf, p0, 0, 0, 0);
;         p1 = __builtin_amdgcn_mfma_f32_32x32x16_bf16(b1, qf, p1, 0, 0, 0); }
; }
; template <bool SBK>
; __device__ __forceinline__ void attn_unit(const Args& a, int l, LAS char* lds, int b, int h8, int P0, int orow0, int nvalid) {
;     ...
;                 { const LAS float* cb_ = cm_l + kb + 4 * hi;
; #pragma unroll
;  for (int g = 0; g < 4; ++g) { const f32x4 c0 = *(const LAS f32x4*)(cb_ + 8 * g);
; #pragma unroll
;  for (int e = 0; e < 4; ++e) p0[4 * g + e] -= c0[e]; }
;                   __builtin_amdgcn_sched_barrier(0);
; #pragma unroll
;  for (int g = 0; g < 4; ++g) { const f32x4 c1 = *(const LAS f32x4*)(cb_ + 32 + 8 * g);
; #pragma unroll
;  for (int e = 0; e < 4; ++e) p1[4 * g + e] -= c1[e]; } }
;                 __builtin_amdgcn_sched_barrier(0);
;                 if (needmask) {
; #pragma unroll
;  for (int r = 0; r < 16; ++r) { const int c = (r & 3) + 8 * (r >> 2); if (dq - c < 0) p0[r] = NEG; if (dq - c - 32 < 0) p1[r] = NEG; } }
.LBB0_569:
	s_sub_i32 s5, s7, s23
	s_lshl_b32 s27, s5, 6
	s_cmp_gt_i32 s27, s8
	s_cbranch_scc1 .LBB0_577
	s_lshl_b32 s35, s4, 14
	v_add_u32_e32 v0, s35, v174
	v_add_u32_e32 v14, v0, v176
	ds_read_b128 v[2:5], v14 offset:49152
	ds_read_b128 v[6:9], v14 offset:49280
	v_add_u32_e32 v15, v0, v177
	v_add_u32_e32 v88, v0, v178
	v_add_u32_e32 v0, v0, v179
	s_or_b32 s4, s27, 63
	s_waitcnt lgkmcnt(0)
	s_setprio 1
	v_mfma_f32_32x32x16_bf16 v[96:111], v[2:5], v[112:115], 0
	ds_read_b128 v[2:5], v15 offset:49152
	ds_read_b128 v[10:13], v15 offset:49280
	ds_read_b128 v[80:83], v88 offset:49280
	s_waitcnt lgkmcnt(0)
	v_mfma_f32_32x32x16_bf16 v[96:111], v[2:5], v[116:119], v[96:111]
	ds_read_b128 v[2:5], v88 offset:49152
	s_waitcnt lgkmcnt(0)
	v_mfma_f32_32x32x16_bf16 v[96:111], v[2:5], v[120:123], v[96:111]
	ds_read_b128 v[2:5], v0 offset:49152
	ds_read_b128 v[84:87], v0 offset:49280
	s_waitcnt lgkmcnt(0)
	v_mfma_f32_32x32x16_bf16 v[96:111], v[2:5], v[124:127], v[96:111]
	v_mfma_f32_32x32x16_bf16 v[96:111], v[6:9], v[128:131], v[96:111]
	v_mfma_f32_32x32x16_bf16 v[96:111], v[10:13], v[132:135], v[96:111]
	ds_read_b128 v[2:5], v14 offset:57344
	ds_read_b128 v[6:9], v14 offset:57472
	ds_read_b128 v[10:13], v15 offset:57344
	ds_read_b128 v[184:187], v15 offset:57472
	ds_read_b128 v[188:191], v88 offset:57344
	ds_read_b128 v[192:195], v88 offset:57472
	ds_read_b128 v[196:199], v0 offset:57344
	ds_read_b128 v[200:203], v0 offset:57472
	v_mfma_f32_32x32x16_bf16 v[96:111], v[80:83], v[136:139], v[96:111]
	v_mfma_f32_32x32x16_bf16 v[96:111], v[84:87], v[140:143], v[96:111]
	s_waitcnt lgkmcnt(0)
	v_mfma_f32_32x32x16_bf16 v[80:95], v[2:5], v[112:115], 0
	v_lshl_add_u32 v0, s27, 2, v180
	v_mfma_f32_32x32x16_bf16 v[80:95], v[10:13], v[116:119], v[80:95]
	v_mfma_f32_32x32x16_bf16 v[80:95], v[188:191], v[120:123], v[80:95]
	v_mfma_f32_32x32x16_bf16 v[80:95], v[196:199], v[124:127], v[80:95]
	v_mfma_f32_32x32x16_bf16 v[80:95], v[6:9], v[128:131], v[80:95]
	v_mfma_f32_32x32x16_bf16 v[80:95], v[184:187], v[132:135], v[80:95]
	v_mfma_f32_32x32x16_bf16 v[80:95], v[192:195], v[136:139], v[80:95]
	ds_read_b128 v[184:187], v0
	ds_read_b128 v[188:191], v0 offset:32
	ds_read_b128 v[192:195], v0 offset:64
	ds_read_b128 v[196:199], v0 offset:96
	v_mfma_f32_32x32x16_bf16 v[80:95], v[200:203], v[140:143], v[80:95]
	s_setprio 0
	ds_read_b128 v[2:5], v0 offset:224
	ds_read_b128 v[6:9], v0 offset:192
	ds_read_b128 v[200:203], v0 offset:128
	ds_read_b128 v[204:207], v0 offset:160
	s_waitcnt lgkmcnt(0)
	v_sub_f32_e32 v97, v97, v185
	s_nop 5
	v_sub_f32_e32 v15, v95, v5
	v_sub_f32_e32 v14, v94, v4
	v_sub_f32_e32 v13, v93, v3
	v_sub_f32_e32 v12, v92, v2
	v_sub_f32_e32 v11, v91, v9
	v_sub_f32_e32 v10, v90, v8
	v_sub_f32_e32 v9, v89, v7
	v_sub_f32_e32 v8, v88, v6
	v_sub_f32_e32 v7, v87, v207
	v_sub_f32_e32 v6, v86, v206
	v_sub_f32_e32 v5, v85, v205
	v_sub_f32_e32 v4, v84, v204
	v_sub_f32_e32 v3, v83, v203
	v_sub_f32_e32 v2, v82, v202
	v_sub_f32_e32 v91, v81, v201
	v_sub_f32_e32 v0, v80, v200
	v_sub_f32_e32 v81, v111, v199
	v_sub_f32_e32 v80, v110, v198
	v_sub_f32_e32 v83, v109, v197
	v_sub_f32_e32 v82, v108, v196
	v_sub_f32_e32 v85, v107, v195
	v_sub_f32_e32 v84, v106, v194
	v_sub_f32_e32 v87, v105, v193
	v_sub_f32_e32 v86, v104, v192
	v_sub_f32_e32 v89, v103, v191
	v_sub_f32_e32 v88, v102, v190
	v_sub_f32_e32 v93, v101, v189
	v_sub_f32_e32 v90, v100, v188
	v_sub_f32_e32 v95, v99, v187
	v_sub_f32_e32 v92, v98, v186
	v_sub_f32_e32 v94, v96, v184
	s_cmp_le_i32 s4, s31
	s_cbranch_scc1 .LBB0_572
	v_or_b32_e32 v96, s27, v172
	v_sub_u32_e32 v98, v155, v96
	v_cmp_lt_i32_e32 vcc, -1, v98
	v_xad_u32 v96, v96, -1, v155
	s_nop 0
	v_cndmask_b32_e32 v94, v245, v94, vcc
	v_cmp_lt_i32_e32 vcc, 31, v98
	s_nop 1
	v_cndmask_b32_e32 v0, v245, v0, vcc
	v_cmp_lt_i32_e32 vcc, -1, v96
	s_nop 1
	v_cndmask_b32_e32 v97, v245, v97, vcc
	v_cmp_lt_i32_e32 vcc, 31, v96
	v_or_b32_e32 v96, s27, v170
	v_sub_u32_e32 v96, v155, v96
	v_cndmask_b32_e32 v91, v245, v91, vcc
	v_cmp_lt_i32_e32 vcc, -1, v96
	s_nop 1
	v_cndmask_b32_e32 v92, v245, v92, vcc
	v_cmp_lt_i32_e32 vcc, 31, v96
	v_or_b32_e32 v96, s27, v169
	v_sub_u32_e32 v96, v155, v96
	v_cndmask_b32_e32 v2, v245, v2, vcc
	v_cmp_lt_i32_e32 vcc, -1, v96
	s_nop 1
	v_cndmask_b32_e32 v95, v245, v95, vcc
	v_cmp_lt_i32_e32 vcc, 31, v96
	v_or_b32_e32 v96, s27, v168
	v_sub_u32_e32 v96, v155, v96
	v_cndmask_b32_e32 v3, v245, v3, vcc
	v_cmp_lt_i32_e32 vcc, -1, v96
	s_nop 1
	v_cndmask_b32_e32 v90, v245, v90, vcc
	v_cmp_lt_i32_e32 vcc, 31, v96
	v_or_b32_e32 v96, s27, v167
	v_sub_u32_e32 v96, v155, v96
	v_cndmask_b32_e32 v4, v245, v4, vcc
	v_cmp_lt_i32_e32 vcc, -1, v96
	s_nop 1
	v_cndmask_b32_e32 v93, v245, v93, vcc
	v_cmp_lt_i32_e32 vcc, 31, v96
	v_or_b32_e32 v96, s27, v165
	v_sub_u32_e32 v96, v155, v96
	v_cndmask_b32_e32 v5, v245, v5, vcc
	v_cmp_lt_i32_e32 vcc, -1, v96
	s_nop 1
	v_cndmask_b32_e32 v88, v245, v88, vcc
	v_cmp_lt_i32_e32 vcc, 31, v96
	v_or_b32_e32 v96, s27, v164
	v_sub_u32_e32 v96, v155, v96
	v_cndmask_b32_e32 v6, v245, v6, vcc
	v_cmp_lt_i32_e32 vcc, -1, v96
	s_nop 1
	v_cndmask_b32_e32 v89, v245, v89, vcc
	v_cmp_lt_i32_e32 vcc, 31, v96
	v_or_b32_e32 v96, s27, v163
	v_sub_u32_e32 v96, v155, v96
	v_cndmask_b32_e32 v7, v245, v7, vcc
	v_cmp_lt_i32_e32 vcc, -1, v96
	s_nop 1
	v_cndmask_b32_e32 v86, v245, v86, vcc
	v_cmp_lt_i32_e32 vcc, 31, v96
	v_or_b32_e32 v96, s27, v162
	v_sub_u32_e32 v96, v155, v96
	v_cndmask_b32_e32 v8, v245, v8, vcc
	v_cmp_lt_i32_e32 vcc, -1, v96
	s_nop 1
	v_cndmask_b32_e32 v87, v245, v87, vcc
	v_cmp_lt_i32_e32 vcc, 31, v96
	v_or_b32_e32 v96, s27, v161
	v_sub_u32_e32 v96, v155, v96
	v_cndmask_b32_e32 v9, v245, v9, vcc
	v_cmp_lt_i32_e32 vcc, -1, v96
	s_nop 1
	v_cndmask_b32_e32 v84, v245, v84, vcc
	v_cmp_lt_i32_e32 vcc, 31, v96
	v_or_b32_e32 v96, s27, v160
	v_sub_u32_e32 v96, v155, v96
	v_cndmask_b32_e32 v10, v245, v10, vcc
	v_cmp_lt_i32_e32 vcc, -1, v96
	s_nop 1
	v_cndmask_b32_e32 v85, v245, v85, vcc
	v_cmp_lt_i32_e32 vcc, 31, v96
	v_or_b32_e32 v96, s27, v159
	v_sub_u32_e32 v96, v155, v96
	v_cndmask_b32_e32 v11, v245, v11, vcc
	v_cmp_lt_i32_e32 vcc, -1, v96
	s_nop 1
	v_cndmask_b32_e32 v82, v245, v82, vcc
	v_cmp_lt_i32_e32 vcc, 31, v96
	v_or_b32_e32 v96, s27, v158
	v_sub_u32_e32 v96, v155, v96
	v_cndmask_b32_e32 v12, v245, v12, vcc
	v_cmp_lt_i32_e32 vcc, -1, v96
	s_nop 1
	v_cndmask_b32_e32 v83, v245, v83, vcc
	v_cmp_lt_i32_e32 vcc, 31, v96
	v_or_b32_e32 v96, s27, v157
	v_sub_u32_e32 v96, v155, v96
	v_cndmask_b32_e32 v13, v245, v13, vcc
	v_cmp_lt_i32_e32 vcc, -1, v96
	s_nop 1
	v_cndmask_b32_e32 v80, v245, v80, vcc
	v_cmp_lt_i32_e32 vcc, 31, v96
	v_or_b32_e32 v96, s27, v156
	v_sub_u32_e32 v96, v155, v96
	v_cndmask_b32_e32 v14, v245, v14, vcc
	v_cmp_lt_i32_e32 vcc, -1, v96
	s_nop 1
	v_cndmask_b32_e32 v81, v245, v81, vcc
	v_cmp_lt_i32_e32 vcc, 31, v96
	s_nop 1
	v_cndmask_b32_e32 v15, v245, v15, vcc

; __device__ __forceinline__ int crow(int r, int hi) { return (r & 3) + 8 * (r >> 2) + 4 * hi; }
; __device__ __forceinline__ float pair_other(float x, int hi) { auto rr = __builtin_amdgcn_permlane32_swap(__float_as_uint(x), __float_as_uint(x), false, false); return __uint_as_float(hi ? rr[0] : rr[1]); }
; #define PV_RD(d0, F) do { constexpr int b_ = v_rd_off(d0, 0, 0); \
;         TRRD(F[0], b_); TRRD(F[1], b_ + 2048); TRRD(F[2], b_ + 4096); TRRD(F[3], b_ + 6144); TRRD(F[4], b_ + 8192); TRRD(F[5], b_ + 10240); TRRD(F[6], b_ + 12288); TRRD(F[7], b_ + 14336); } while (0)
; #define LGK(n) do { asm volatile("s_waitcnt lgkmcnt(" #n ")" ::: "memory"); __builtin_amdgcn_sched_barrier(0); } while (0)
; __device__ __forceinline__ void pv_tile(f32x16* o, int vb0  , bf16x8 pa0, bf16x8 pa1, bf16x8 pa2, bf16x8 pa3) {
;     ...
;     s16x4 fa[8], fb[8];
;     PV_RD(0, fa); PV_RD(1, fb);
;     LGK(8); PV_MM(0, fa); __builtin_amdgcn_sched_barrier(0);
;     PV_RD(2, fa);
;     LGK(8); PV_MM(1, fb); __builtin_amdgcn_sched_barrier(0);
;     PV_RD(3, fb);
;     LGK(8); PV_MM(2, fa); __builtin_amdgcn_sched_barrier(0);
;     LGK(0); PV_MM(3, fb);
;     ...
; }
; template <bool SBK>
; __device__ __forceinline__ void attn_unit(const Args& a, int l, LAS char* lds, int b, int h8, int P0, int orow0, int nvalid) {
;     ...
;                 ps += pair_other(ps, hi); l_reg = l_reg * alpha + ps;
;                 if (__any(alpha < 1.f)) { if (hi == 0) al_l[r32] = alpha; asm volatile("s_waitcnt lgkmcnt(0)" ::: "memory");
; #pragma unroll
;  for (int r = 0; r < 16; ++r) { const float av = al_l[crow(r, hi)]; o[0][r] *= av; o[1][r] *= av; o[2][r] *= av; o[3][r] *= av; } }
;             }
;             PK4(p0, 0, pa0); PK4(p0, 8, pa1); PK4(p1, 0, pa2); PK4(p1, 8, pa3);
;             pv_tile(o, vb0 + vb * SHM_V, pa0, pa1, pa2, pa3);
.LBB0_576:
	v_cvt_pk_bf16_f32 v88, v88, v89
	v_cvt_pk_bf16_f32 v89, v90, v91
	v_cvt_pk_bf16_f32 v90, v92, v93
	v_cvt_pk_bf16_f32 v91, v94, v97
	v_cvt_pk_bf16_f32 v92, v95, v87
	v_cvt_pk_bf16_f32 v93, v84, v85
	v_cvt_pk_bf16_f32 v94, v82, v83
	v_cvt_pk_bf16_f32 v95, v80, v81
	v_cvt_pk_bf16_f32 v2, v0, v2
	v_cvt_pk_bf16_f32 v3, v3, v4
	v_cvt_pk_bf16_f32 v4, v5, v6
	v_cvt_pk_bf16_f32 v5, v7, v86
	v_cvt_pk_bf16_f32 v6, v8, v9
	v_cvt_pk_bf16_f32 v7, v10, v11
	v_cvt_pk_bf16_f32 v8, v12, v13
	v_cvt_pk_bf16_f32 v9, v14, v15
	v_add_u32_e32 v0, s35, v181
	ds_read_b64_tr_b16 v[10:11], v0 offset:0
	ds_read_b64_tr_b16 v[12:13], v0 offset:0x800
	ds_read_b64_tr_b16 v[80:81], v0 offset:0x1000
	ds_read_b64_tr_b16 v[82:83], v0 offset:0x1800
	v_cndmask_b32_e64 v100, v100, v101, s[38:39]
	ds_read_b64_tr_b16 v[84:85], v0 offset:0x2000
	v_add_f32_e32 v110, v99, v100
	ds_read_b64_tr_b16 v[86:87], v0 offset:0x2800
	v_fmac_f32_e32 v110, v182, v98
	ds_read_b64_tr_b16 v[98:99], v0 offset:0x3000
	ds_read_b64_tr_b16 v[100:101], v0 offset:0x3800
	ds_read_b64_tr_b16 v[102:103], v0 offset:0x200
	ds_read_b64_tr_b16 v[104:105], v0 offset:0xa00
	ds_read_b64_tr_b16 v[106:107], v0 offset:0x1200
	ds_read_b64_tr_b16 v[108:109], v0 offset:0x1a00
	ds_read_b64_tr_b16 v[182:183], v0 offset:0x2200
	ds_read_b64_tr_b16 v[184:185], v0 offset:0x2a00
	ds_read_b64_tr_b16 v[186:187], v0 offset:0x3200
	ds_read_b64_tr_b16 v[188:189], v0 offset:0x3a00
	s_waitcnt lgkmcnt(8)
	v_permlane32_swap_b32_e32 v88, v90
	v_permlane32_swap_b32_e32 v89, v91
	v_permlane32_swap_b32_e32 v92, v94
	v_permlane32_swap_b32_e32 v93, v95
	v_permlane32_swap_b32_e32 v2, v4
	v_permlane32_swap_b32_e32 v3, v5
	v_permlane32_swap_b32_e32 v6, v8
	v_permlane32_swap_b32_e32 v7, v9
	s_setprio 1
	v_mfma_f32_32x32x16_bf16 v[64:79], v[88:91], v[10:13], v[64:79]
	v_mfma_f32_32x32x16_bf16 v[64:79], v[92:95], v[80:83], v[64:79]
	v_mfma_f32_32x32x16_bf16 v[64:79], v[2:5], v[84:87], v[64:79]
	v_mfma_f32_32x32x16_bf16 v[64:79], v[6:9], v[98:101], v[64:79]
	ds_read_b64_tr_b16 v[10:11], v0 offset:0x400
	ds_read_b64_tr_b16 v[12:13], v0 offset:0xc00
	ds_read_b64_tr_b16 v[80:81], v0 offset:0x1400
	ds_read_b64_tr_b16 v[82:83], v0 offset:0x1c00
	ds_read_b64_tr_b16 v[84:85], v0 offset:0x2400
	ds_read_b64_tr_b16 v[86:87], v0 offset:0x2c00
	ds_read_b64_tr_b16 v[98:99], v0 offset:0x3400
	ds_read_b64_tr_b16 v[100:101], v0 offset:0x3c00
	s_waitcnt lgkmcnt(8)
	v_mfma_f32_32x32x16_bf16 v[32:47], v[88:91], v[102:105], v[32:47]
	v_mfma_f32_32x32x16_bf16 v[32:47], v[92:95], v[106:109], v[32:47]
	v_mfma_f32_32x32x16_bf16 v[32:47], v[2:5], v[182:185], v[32:47]
	v_mfma_f32_32x32x16_bf16 v[32:47], v[6:9], v[186:189], v[32:47]
	ds_read_b64_tr_b16 v[102:103], v0 offset:0x600
	ds_read_b64_tr_b16 v[104:105], v0 offset:0xe00
	ds_read_b64_tr_b16 v[106:107], v0 offset:0x1600
	ds_read_b64_tr_b16 v[108:109], v0 offset:0x1e00
	ds_read_b64_tr_b16 v[182:183], v0 offset:0x2600
	ds_read_b64_tr_b16 v[184:185], v0 offset:0x2e00
	ds_read_b64_tr_b16 v[186:187], v0 offset:0x3600
	ds_read_b64_tr_b16 v[188:189], v0 offset:0x3e00
	s_waitcnt lgkmcnt(8)
	v_mfma_f32_32x32x16_bf16 v[48:63], v[88:91], v[10:13], v[48:63]
	v_mfma_f32_32x32x16_bf16 v[48:63], v[92:95], v[80:83], v[48:63]
	v_mfma_f32_32x32x16_bf16 v[48:63], v[2:5], v[84:87], v[48:63]
	v_mfma_f32_32x32x16_bf16 v[48:63], v[6:9], v[98:101], v[48:63]
	s_waitcnt lgkmcnt(0)
	v_mfma_f32_32x32x16_bf16 v[16:31], v[88:91], v[102:105], v[16:31]
	v_mfma_f32_32x32x16_bf16 v[16:31], v[92:95], v[106:109], v[16:31]
	v_mfma_f32_32x32x16_bf16 v[16:31], v[2:5], v[182:185], v[16:31]
	v_mov_b32_e32 v182, v110
	v_mfma_f32_32x32x16_bf16 v[16:31], v[6:9], v[186:189], v[16:31]
	s_setprio 0
	s_cmp_le_u32 s7, s23
	v_mov_b32_e32 v0, 0
	s_cbranch_scc0 .LBB0_578
	s_branch .LBB0_579

; #define LAS __attribute__((address_space(3)))
; __device__ __forceinline__ void qkt(f32x16& p0, f32x16& p1, const LAS char* K_buf, int r32, int hi, const bf16x8* qr) {
;     p0 = f32x16{}; p1 = f32x16{};
;     const LAS char* kb[4];
; #pragma unroll
;     for (int dd = 0; dd < 4; ++dd) kb[dd] = K_buf + KSWZ(r32, (dd * 16 + hi * 8) * 2);
; #pragma unroll
;     for (int d0 = 0; d0 < 8; ++d0) { const LAS char* ap = kb[d0 & 3] + (d0 >> 2) * 128;
;         const bf16x8 b0 = *(const LAS bf16x8*)ap;
;         const bf16x8 b1 = *(const LAS bf16x8*)(ap + 32 * 256);
;         const bf16x8 qf = qr[d0];
;         p0 = __builtin_amdgcn_mfma_f32_32x32x16_bf16(b0, qf, p0, 0, 0, 0);
;         p1 = __builtin_amdgcn_mfma_f32_32x32x16_bf16(b1, qf, p1, 0, 0, 0); }
; }
; template <bool SBK>
; __device__ __forceinline__ void attn_unit(const Args& a, int l, LAS char* lds, int b, int h8, int P0, int orow0, int nvalid) {
;     ...
;                 { const LAS float* cb_ = cm_l + kb + 4 * hi;
; #pragma unroll
;  for (int g = 0; g < 4; ++g) { const f32x4 c0 = *(const LAS f32x4*)(cb_ + 8 * g);
; #pragma unroll
;  for (int e = 0; e < 4; ++e) p0[4 * g + e] -= c0[e]; }
;                   __builtin_amdgcn_sched_barrier(0);
; #pragma unroll
;  for (int g = 0; g < 4; ++g) { const f32x4 c1 = *(const LAS f32x4*)(cb_ + 32 + 8 * g);
; #pragma unroll
;  for (int e = 0; e < 4; ++e) p1[4 * g + e] -= c1[e]; } }
;                 __builtin_amdgcn_sched_barrier(0);
;                 if (needmask) {
; #pragma unroll
;  for (int r = 0; r < 16; ++r) { const int c = (r & 3) + 8 * (r >> 2); if (dq - c < 0) p0[r] = NEG; if (dq - c - 32 < 0) p1[r] = NEG; } }
.LBB0_704:
	s_lshl_b32 s23, s7, 6
	s_sub_i32 s26, 0xc0, s23
	s_cmp_gt_i32 s26, s5
	s_cbranch_scc1 .LBB0_712
	s_lshl_b32 s27, s22, 14
	v_add_u32_e32 v0, s27, v174
	v_add_u32_e32 v14, v0, v176
	ds_read_b128 v[2:5], v14 offset:49152
	ds_read_b128 v[6:9], v14 offset:49280
	v_add_u32_e32 v15, v0, v177
	v_add_u32_e32 v88, v0, v178
	v_add_u32_e32 v0, v0, v179
	s_or_b32 s22, s26, 63
	s_waitcnt lgkmcnt(0)
	s_setprio 1
	v_mfma_f32_32x32x16_bf16 v[96:111], v[2:5], v[112:115], 0
	ds_read_b128 v[2:5], v15 offset:49152
	ds_read_b128 v[10:13], v15 offset:49280
	ds_read_b128 v[80:83], v88 offset:49280
	s_waitcnt lgkmcnt(0)
	v_mfma_f32_32x32x16_bf16 v[96:111], v[2:5], v[116:119], v[96:111]
	ds_read_b128 v[2:5], v88 offset:49152
	s_waitcnt lgkmcnt(0)
	v_mfma_f32_32x32x16_bf16 v[96:111], v[2:5], v[120:123], v[96:111]
	ds_read_b128 v[2:5], v0 offset:49152
	ds_read_b128 v[84:87], v0 offset:49280
	s_waitcnt lgkmcnt(0)
	v_mfma_f32_32x32x16_bf16 v[96:111], v[2:5], v[124:127], v[96:111]
	v_mfma_f32_32x32x16_bf16 v[96:111], v[6:9], v[128:131], v[96:111]
	v_mfma_f32_32x32x16_bf16 v[96:111], v[10:13], v[132:135], v[96:111]
	ds_read_b128 v[2:5], v14 offset:57344
	ds_read_b128 v[6:9], v14 offset:57472
	ds_read_b128 v[10:13], v15 offset:57344
	ds_read_b128 v[184:187], v15 offset:57472
	ds_read_b128 v[188:191], v88 offset:57344
	ds_read_b128 v[192:195], v88 offset:57472
	ds_read_b128 v[196:199], v0 offset:57344
	ds_read_b128 v[200:203], v0 offset:57472
	v_mfma_f32_32x32x16_bf16 v[96:111], v[80:83], v[136:139], v[96:111]
	v_mfma_f32_32x32x16_bf16 v[96:111], v[84:87], v[140:143], v[96:111]
	s_waitcnt lgkmcnt(0)
	v_mfma_f32_32x32x16_bf16 v[80:95], v[2:5], v[112:115], 0
	s_lshl_b32 s23, s23, 2
	v_subrev_u32_e32 v0, s23, v180
	v_mfma_f32_32x32x16_bf16 v[80:95], v[10:13], v[116:119], v[80:95]
	v_mfma_f32_32x32x16_bf16 v[80:95], v[188:191], v[120:123], v[80:95]
	v_mfma_f32_32x32x16_bf16 v[80:95], v[196:199], v[124:127], v[80:95]
	v_mfma_f32_32x32x16_bf16 v[80:95], v[6:9], v[128:131], v[80:95]
	v_mfma_f32_32x32x16_bf16 v[80:95], v[184:187], v[132:135], v[80:95]
	v_mfma_f32_32x32x16_bf16 v[80:95], v[192:195], v[136:139], v[80:95]
	ds_read_b128 v[184:187], v0 offset:768
	ds_read_b128 v[188:191], v0 offset:800
	ds_read_b128 v[192:195], v0 offset:832
	ds_read_b128 v[196:199], v0 offset:864
	v_mfma_f32_32x32x16_bf16 v[80:95], v[200:203], v[140:143], v[80:95]
	s_setprio 0
	ds_read_b128 v[2:5], v0 offset:992
	ds_read_b128 v[6:9], v0 offset:960
	ds_read_b128 v[200:203], v0 offset:896
	ds_read_b128 v[204:207], v0 offset:928
	s_waitcnt lgkmcnt(0)
	v_sub_f32_e32 v97, v97, v185
	s_nop 5
	v_sub_f32_e32 v15, v95, v5
	v_sub_f32_e32 v14, v94, v4
	v_sub_f32_e32 v13, v93, v3
	v_sub_f32_e32 v12, v92, v2
	v_sub_f32_e32 v11, v91, v9
	v_sub_f32_e32 v10, v90, v8
	v_sub_f32_e32 v9, v89, v7
	v_sub_f32_e32 v8, v88, v6
	v_sub_f32_e32 v7, v87, v207
	v_sub_f32_e32 v6, v86, v206
	v_sub_f32_e32 v5, v85, v205
	v_sub_f32_e32 v4, v84, v204
	v_sub_f32_e32 v3, v83, v203
	v_sub_f32_e32 v2, v82, v202
	v_sub_f32_e32 v91, v81, v201
	v_sub_f32_e32 v0, v80, v200
	v_sub_f32_e32 v81, v111, v199
	v_sub_f32_e32 v80, v110, v198
	v_sub_f32_e32 v83, v109, v197
	v_sub_f32_e32 v82, v108, v196
	v_sub_f32_e32 v85, v107, v195
	v_sub_f32_e32 v84, v106, v194
	v_sub_f32_e32 v87, v105, v193
	v_sub_f32_e32 v86, v104, v192
	v_sub_f32_e32 v89, v103, v191
	v_sub_f32_e32 v88, v102, v190
	v_sub_f32_e32 v93, v101, v189
	v_sub_f32_e32 v90, v100, v188
	v_sub_f32_e32 v95, v99, v187
	v_sub_f32_e32 v92, v98, v186
	v_sub_f32_e32 v94, v96, v184
	s_cmp_le_i32 s22, s4
	s_cbranch_scc1 .LBB0_707
	v_or_b32_e32 v96, s26, v171
	v_sub_u32_e32 v98, v155, v96
	v_cmp_lt_i32_e32 vcc, -1, v98
	v_xad_u32 v96, v96, -1, v155
	s_nop 0
	v_cndmask_b32_e32 v94, v245, v94, vcc
	v_cmp_lt_i32_e32 vcc, 31, v98
	s_nop 1
	v_cndmask_b32_e32 v0, v245, v0, vcc
	v_cmp_lt_i32_e32 vcc, -1, v96
	s_nop 1
	v_cndmask_b32_e32 v97, v245, v97, vcc
	v_cmp_lt_i32_e32 vcc, 31, v96
	v_or_b32_e32 v96, s26, v170
	v_sub_u32_e32 v96, v155, v96
	v_cndmask_b32_e32 v91, v245, v91, vcc
	v_cmp_lt_i32_e32 vcc, -1, v96
	s_nop 1
	v_cndmask_b32_e32 v92, v245, v92, vcc
	v_cmp_lt_i32_e32 vcc, 31, v96
	v_or_b32_e32 v96, s26, v169
	v_sub_u32_e32 v96, v155, v96
	v_cndmask_b32_e32 v2, v245, v2, vcc
	v_cmp_lt_i32_e32 vcc, -1, v96
	s_nop 1
	v_cndmask_b32_e32 v95, v245, v95, vcc
	v_cmp_lt_i32_e32 vcc, 31, v96
	v_or_b32_e32 v96, s26, v168
	v_sub_u32_e32 v96, v155, v96
	v_cndmask_b32_e32 v3, v245, v3, vcc
	v_cmp_lt_i32_e32 vcc, -1, v96
	s_nop 1
	v_cndmask_b32_e32 v90, v245, v90, vcc
	v_cmp_lt_i32_e32 vcc, 31, v96
	v_or_b32_e32 v96, s26, v166
	v_sub_u32_e32 v96, v155, v96
	v_cndmask_b32_e32 v4, v245, v4, vcc
	v_cmp_lt_i32_e32 vcc, -1, v96
	s_nop 1
	v_cndmask_b32_e32 v93, v245, v93, vcc
	v_cmp_lt_i32_e32 vcc, 31, v96
	v_or_b32_e32 v96, s26, v165
	v_sub_u32_e32 v96, v155, v96
	v_cndmask_b32_e32 v5, v245, v5, vcc
	v_cmp_lt_i32_e32 vcc, -1, v96
	s_nop 1
	v_cndmask_b32_e32 v88, v245, v88, vcc
	v_cmp_lt_i32_e32 vcc, 31, v96
	v_or_b32_e32 v96, s26, v164
	v_sub_u32_e32 v96, v155, v96
	v_cndmask_b32_e32 v6, v245, v6, vcc
	v_cmp_lt_i32_e32 vcc, -1, v96
	s_nop 1
	v_cndmask_b32_e32 v89, v245, v89, vcc
	v_cmp_lt_i32_e32 vcc, 31, v96
	v_or_b32_e32 v96, s26, v163
	v_sub_u32_e32 v96, v155, v96
	v_cndmask_b32_e32 v7, v245, v7, vcc
	v_cmp_lt_i32_e32 vcc, -1, v96
	s_nop 1
	v_cndmask_b32_e32 v86, v245, v86, vcc
	v_cmp_lt_i32_e32 vcc, 31, v96
	v_or_b32_e32 v96, s26, v162
	v_sub_u32_e32 v96, v155, v96
	v_cndmask_b32_e32 v8, v245, v8, vcc
	v_cmp_lt_i32_e32 vcc, -1, v96
	s_nop 1
	v_cndmask_b32_e32 v87, v245, v87, vcc
	v_cmp_lt_i32_e32 vcc, 31, v96
	v_or_b32_e32 v96, s26, v161
	v_sub_u32_e32 v96, v155, v96
	v_cndmask_b32_e32 v9, v245, v9, vcc
	v_cmp_lt_i32_e32 vcc, -1, v96
	s_nop 1
	v_cndmask_b32_e32 v84, v245, v84, vcc
	v_cmp_lt_i32_e32 vcc, 31, v96
	v_or_b32_e32 v96, s26, v160
	v_sub_u32_e32 v96, v155, v96
	v_cndmask_b32_e32 v10, v245, v10, vcc
	v_cmp_lt_i32_e32 vcc, -1, v96
	s_nop 1
	v_cndmask_b32_e32 v85, v245, v85, vcc
	v_cmp_lt_i32_e32 vcc, 31, v96
	v_or_b32_e32 v96, s26, v159
	v_sub_u32_e32 v96, v155, v96
	v_cndmask_b32_e32 v11, v245, v11, vcc
	v_cmp_lt_i32_e32 vcc, -1, v96
	s_nop 1
	v_cndmask_b32_e32 v82, v245, v82, vcc
	v_cmp_lt_i32_e32 vcc, 31, v96
	v_or_b32_e32 v96, s26, v158
	v_sub_u32_e32 v96, v155, v96
	v_cndmask_b32_e32 v12, v245, v12, vcc
	v_cmp_lt_i32_e32 vcc, -1, v96
	s_nop 1
	v_cndmask_b32_e32 v83, v245, v83, vcc
	v_cmp_lt_i32_e32 vcc, 31, v96
	v_or_b32_e32 v96, s26, v157
	v_sub_u32_e32 v96, v155, v96
	v_cndmask_b32_e32 v13, v245, v13, vcc
	v_cmp_lt_i32_e32 vcc, -1, v96
	s_nop 1
	v_cndmask_b32_e32 v80, v245, v80, vcc
	v_cmp_lt_i32_e32 vcc, 31, v96
	v_or_b32_e32 v96, s26, v156
	v_sub_u32_e32 v96, v155, v96
	v_cndmask_b32_e32 v14, v245, v14, vcc
	v_cmp_lt_i32_e32 vcc, -1, v96
	s_nop 1
	v_cndmask_b32_e32 v81, v245, v81, vcc
	v_cmp_lt_i32_e32 vcc, 31, v96
	s_nop 1
	v_cndmask_b32_e32 v15, v245, v15, vcc

; __device__ __forceinline__ int crow(int r, int hi) { return (r & 3) + 8 * (r >> 2) + 4 * hi; }
; __device__ __forceinline__ float pair_other(float x, int hi) { auto rr = __builtin_amdgcn_permlane32_swap(__float_as_uint(x), __float_as_uint(x), false, false); return __uint_as_float(hi ? rr[0] : rr[1]); }
; #define PV_RD(d0, F) do { constexpr int b_ = v_rd_off(d0, 0, 0); \
;         TRRD(F[0], b_); TRRD(F[1], b_ + 2048); TRRD(F[2], b_ + 4096); TRRD(F[3], b_ + 6144); TRRD(F[4], b_ + 8192); TRRD(F[5], b_ + 10240); TRRD(F[6], b_ + 12288); TRRD(F[7], b_ + 14336); } while (0)
; #define LGK(n) do { asm volatile("s_waitcnt lgkmcnt(" #n ")" ::: "memory"); __builtin_amdgcn_sched_barrier(0); } while (0)
; __device__ __forceinline__ void pv_tile(f32x16* o, int vb0  , bf16x8 pa0, bf16x8 pa1, bf16x8 pa2, bf16x8 pa3) {
;     ...
;     s16x4 fa[8], fb[8];
;     PV_RD(0, fa); PV_RD(1, fb);
;     LGK(8); PV_MM(0, fa); __builtin_amdgcn_sched_barrier(0);
;     PV_RD(2, fa);
;     LGK(8); PV_MM(1, fb); __builtin_amdgcn_sched_barrier(0);
;     PV_RD(3, fb);
;     LGK(8); PV_MM(2, fa); __builtin_amdgcn_sched_barrier(0);
;     LGK(0); PV_MM(3, fb);
;     ...
; }
; template <bool SBK>
; __device__ __forceinline__ void attn_unit(const Args& a, int l, LAS char* lds, int b, int h8, int P0, int orow0, int nvalid) {
;     ...
;                 ps += pair_other(ps, hi); l_reg = l_reg * alpha + ps;
;                 if (__any(alpha < 1.f)) { if (hi == 0) al_l[r32] = alpha; asm volatile("s_waitcnt lgkmcnt(0)" ::: "memory");
; #pragma unroll
;  for (int r = 0; r < 16; ++r) { const float av = al_l[crow(r, hi)]; o[0][r] *= av; o[1][r] *= av; o[2][r] *= av; o[3][r] *= av; } }
;             }
;             PK4(p0, 0, pa0); PK4(p0, 8, pa1); PK4(p1, 0, pa2); PK4(p1, 8, pa3);
;             pv_tile(o, vb0 + vb * SHM_V, pa0, pa1, pa2, pa3);
.LBB0_711:
	v_cvt_pk_bf16_f32 v88, v88, v89
	v_cvt_pk_bf16_f32 v89, v90, v91
	v_cvt_pk_bf16_f32 v90, v92, v93
	v_cvt_pk_bf16_f32 v91, v94, v97
	v_cvt_pk_bf16_f32 v92, v95, v87
	v_cvt_pk_bf16_f32 v93, v84, v85
	v_cvt_pk_bf16_f32 v94, v82, v83
	v_cvt_pk_bf16_f32 v95, v80, v81
	v_cvt_pk_bf16_f32 v2, v0, v2
	v_cvt_pk_bf16_f32 v3, v3, v4
	v_cvt_pk_bf16_f32 v4, v5, v6
	v_cvt_pk_bf16_f32 v5, v7, v86
	v_cvt_pk_bf16_f32 v6, v8, v9
	v_cvt_pk_bf16_f32 v7, v10, v11
	v_cvt_pk_bf16_f32 v8, v12, v13
	v_cvt_pk_bf16_f32 v9, v14, v15
	v_add_u32_e32 v0, s27, v181
	ds_read_b64_tr_b16 v[10:11], v0 offset:0
	ds_read_b64_tr_b16 v[12:13], v0 offset:0x800
	ds_read_b64_tr_b16 v[80:81], v0 offset:0x1000
	ds_read_b64_tr_b16 v[82:83], v0 offset:0x1800
	v_cndmask_b32_e64 v100, v100, v101, s[38:39]
	ds_read_b64_tr_b16 v[84:85], v0 offset:0x2000
	v_add_f32_e32 v110, v99, v100
	ds_read_b64_tr_b16 v[86:87], v0 offset:0x2800
	v_fmac_f32_e32 v110, v182, v98
	ds_read_b64_tr_b16 v[98:99], v0 offset:0x3000
	ds_read_b64_tr_b16 v[100:101], v0 offset:0x3800
	ds_read_b64_tr_b16 v[102:103], v0 offset:0x200
	ds_read_b64_tr_b16 v[104:105], v0 offset:0xa00
	ds_read_b64_tr_b16 v[106:107], v0 offset:0x1200
	ds_read_b64_tr_b16 v[108:109], v0 offset:0x1a00
	ds_read_b64_tr_b16 v[182:183], v0 offset:0x2200
	ds_read_b64_tr_b16 v[184:185], v0 offset:0x2a00
	ds_read_b64_tr_b16 v[186:187], v0 offset:0x3200
	ds_read_b64_tr_b16 v[188:189], v0 offset:0x3a00
	s_waitcnt lgkmcnt(8)
	v_permlane32_swap_b32_e32 v88, v90
	v_permlane32_swap_b32_e32 v89, v91
	v_permlane32_swap_b32_e32 v92, v94
	v_permlane32_swap_b32_e32 v93, v95
	v_permlane32_swap_b32_e32 v2, v4
	v_permlane32_swap_b32_e32 v3, v5
	v_permlane32_swap_b32_e32 v6, v8
	v_permlane32_swap_b32_e32 v7, v9
	s_setprio 1
	v_mfma_f32_32x32x16_bf16 v[64:79], v[88:91], v[10:13], v[64:79]
	v_mfma_f32_32x32x16_bf16 v[64:79], v[92:95], v[80:83], v[64:79]
	v_mfma_f32_32x32x16_bf16 v[64:79], v[2:5], v[84:87], v[64:79]
	v_mfma_f32_32x32x16_bf16 v[64:79], v[6:9], v[98:101], v[64:79]
	ds_read_b64_tr_b16 v[10:11], v0 offset:0x400
	ds_read_b64_tr_b16 v[12:13], v0 offset:0xc00
	ds_read_b64_tr_b16 v[80:81], v0 offset:0x1400
	ds_read_b64_tr_b16 v[82:83], v0 offset:0x1c00
	ds_read_b64_tr_b16 v[84:85], v0 offset:0x2400
	ds_read_b64_tr_b16 v[86:87], v0 offset:0x2c00
	ds_read_b64_tr_b16 v[98:99], v0 offset:0x3400
	ds_read_b64_tr_b16 v[100:101], v0 offset:0x3c00
	s_waitcnt lgkmcnt(8)
	v_mfma_f32_32x32x16_bf16 v[32:47], v[88:91], v[102:105], v[32:47]
	v_mfma_f32_32x32x16_bf16 v[32:47], v[92:95], v[106:109], v[32:47]
	v_mfma_f32_32x32x16_bf16 v[32:47], v[2:5], v[182:185], v[32:47]
	v_mfma_f32_32x32x16_bf16 v[32:47], v[6:9], v[186:189], v[32:47]
	ds_read_b64_tr_b16 v[102:103], v0 offset:0x600
	ds_read_b64_tr_b16 v[104:105], v0 offset:0xe00
	ds_read_b64_tr_b16 v[106:107], v0 offset:0x1600
	ds_read_b64_tr_b16 v[108:109], v0 offset:0x1e00
	ds_read_b64_tr_b16 v[182:183], v0 offset:0x2600
	ds_read_b64_tr_b16 v[184:185], v0 offset:0x2e00
	ds_read_b64_tr_b16 v[186:187], v0 offset:0x3600
	ds_read_b64_tr_b16 v[188:189], v0 offset:0x3e00
	s_waitcnt lgkmcnt(8)
	v_mfma_f32_32x32x16_bf16 v[48:63], v[88:91], v[10:13], v[48:63]
	v_mfma_f32_32x32x16_bf16 v[48:63], v[92:95], v[80:83], v[48:63]
	v_mfma_f32_32x32x16_bf16 v[48:63], v[2:5], v[84:87], v[48:63]
	v_mfma_f32_32x32x16_bf16 v[48:63], v[6:9], v[98:101], v[48:63]
	s_waitcnt lgkmcnt(0)
	v_mfma_f32_32x32x16_bf16 v[16:31], v[88:91], v[102:105], v[16:31]
	v_mfma_f32_32x32x16_bf16 v[16:31], v[92:95], v[106:109], v[16:31]
	v_mfma_f32_32x32x16_bf16 v[16:31], v[2:5], v[182:185], v[16:31]
	v_mov_b32_e32 v182, v110
	v_mfma_f32_32x32x16_bf16 v[16:31], v[6:9], v[186:189], v[16:31]
	s_setprio 0
	s_cmp_gt_u32 s7, 2
	v_mov_b32_e32 v0, 0
	s_cbranch_scc0 .LBB0_713
	s_branch .LBB0_714
